# V^T b128 re-layout on MLA and FoX attention (not stick-breaking)
# baseline (speedup 1.0000x reference)
; DI int otid() { int t = threadIdx.x; asm volatile("" : "+v"(t)); return t; }
; DI unsigned xb_xcc_id() { return (unsigned)__builtin_amdgcn_s_getreg((3 << 11) | 20) & 0xFu; }
;   constexpr int DQK = (MODE == 1) ? 96 : 64, NKS = DQK / 16, KST = DQK + 8;
;   constexpr int KCH = (MODE == 1) ? 3 : 2;
;   const int t = otid(), lane = t & 63, w = t >> 6, r = lane & 31, hh = lane >> 5;
;   bf16_t* Kl = smem;
;   bf16_t* Vl = smem + 2 * 64 * KST;
;   float* Fl = (float*)(Vl + 2 * 64 * VST);
;   int* s_item = (int*)(Fl + 128);
;   int* s_flag = s_item + 4;
;   const int total = NB * NH * 65;
;   const int lkey = t >> 2, lsub = t & 3;
;   constexpr float LOG2E = 1.44269504f;
;   const float c2 = (MODE == 1 ? 0.10206207f : 0.125f) * LOG2E;
;   const int myx = (int)(xb_xcc_id() & 7u);
;     ...
;     auto lstore = [&](const u32x4 (&rk)[KCH], const u32x4 (&rv)[2], const float rf, int buf) {
;       bf16_t* kd = Kl + buf * 64 * KST + lkey * KST + lsub * 8;
;       *(u32x4*)kd = rk[0]; *(u32x4*)(kd + 32) = rk[1];
;       if (MODE == 1) *(u32x4*)(kd + 64) = rk[KCH - 1];
;       bf16_t* vd = Vl + buf * 64 * VST + lkey * VST + lsub * 8;
;       u32x2 lo, hi;
;       lo[0] = rv[0][0]; lo[1] = rv[0][1]; hi[0] = rv[0][2]; hi[1] = rv[0][3];
;       *(u32x2*)vd = lo; *(u32x2*)(vd + 4) = hi;
;       lo[0] = rv[1][0]; lo[1] = rv[1][1]; hi[0] = rv[1][2]; hi[1] = rv[1][3];
;       *(u32x2*)(vd + 32) = lo; *(u32x2*)(vd + 36) = hi;
;       if (MODE == 2 && t < 64) Fl[buf * 64 + t] = -rf * LOG2E;
;     };
.LBB0_1106:
	s_andn2_b64 vcc, exec, s[4:5]
	s_cbranch_vccnz .LBB0_1209
	v_mov_b32_e32 v1, v172
	s_movk_i32 s1, 0x90
	v_and_b32_e32 v3, 63, v1
	v_ashrrev_i32_e32 v4, 6, v1
	v_and_b32_e32 v5, 31, v1
	v_bfe_u32 v6, v1, 5, 1
	s_waitcnt vmcnt(3)
	v_ashrrev_i32_e32 v115, 2, v1
	v_cmp_eq_u32_e64 s[42:43], 0, v1
	v_lshlrev_b32_e32 v1, 3, v1
	v_and_b32_e32 v2, 24, v1
	v_lshlrev_b32_e32 v144, 1, v2
	v_mad_u64_u32 v[112:113], s[4:5], v115, s1, v[144:145]
	v_lshlrev_b32_e32 v1, 3, v115
	v_readlane_b32 s4, v228, 18
	v_sub_u32_e32 v135, v112, v1
	v_lshrrev_b32_e32 v230, 2, v172
	v_mul_u32_u24_e32 v135, 0x90, v230
	v_bfe_u32 v230, v172, 1, 1
	v_lshl_add_u32 v135, v230, 5, v135
	v_and_b32_e32 v230, 1, v172
	v_lshl_add_u32 v135, v230, 3, v135
	v_mul_u32_u24_e32 v1, 0x48, v5
	v_readlane_b32 s5, v228, 19
	v_cmp_eq_u32_e64 s[44:45], 0, v3
	v_lshlrev_b32_e32 v1, 1, v1
	v_cmp_gt_u32_e64 s[46:47], 32, v3
	v_lshlrev_b32_e32 v3, 3, v5
	s_waitcnt vmcnt(2)
	v_lshl_add_u64 v[116:117], s[4:5], 0, v[144:145]
	v_readlane_b32 s4, v228, 23
	v_lshlrev_b32_e32 v0, 3, v6
	v_lshl_add_u32 v137, v6, 4, v1
	v_sub_u32_e32 v1, v1, v3
	v_readlane_b32 s5, v228, 24
	s_getreg_b32 s37, hwreg(HW_REG_XCC_ID, 0, 4)
	s_mov_b32 s33, 0
	s_waitcnt vmcnt(1)
	v_or_b32_e32 v123, 0x2000, v5
	v_lshlrev_b32_e32 v134, 5, v4
	v_lshlrev_b32_e32 v136, 2, v4
	v_lshlrev_b32_e32 v114, 2, v6
	v_add_u32_e32 v138, v1, v0
	v_and_b32_e32 v230, 31, v172
	v_mul_u32_u24_e32 v138, 0x90, v230
	v_bfe_u32 v230, v172, 5, 1
	v_lshl_add_u32 v138, v230, 4, v138
	v_lshl_add_u64 v[118:119], s[4:5], 0, v[144:145]
	v_lshlrev_b32_e32 v144, 1, v0
	v_lshlrev_b32_e32 v120, 1, v2
	s_branch .LBB0_1109

;     ...
;     __syncthreads();
;     const int enc = s_item[0]; qx = s_item[1];
;     if (enc < 0) break;
;     const int xx_ = enc & 7, idx = enc >> 3;
;     const int qt = 64 - idx % 65, bh = (idx / 65) * 8 + xx_, b = bh >> 4, hd = bh & 15;
;     const int q0 = qt * 128;
;     const int posq = q0 + w * 32 + r;
;     const bool qvalid = posq < L;
;     const int pq = qvalid ? posq : L - 1;
;     bf16_t* qptr = aa.q + (size_t)(b * L + pq) * aa.ldq + hd * aa.hs;
;     bf16x8 qf[NKS];
; #pragma unroll
;     for (int ks = 0; ks < NKS; ++ks) qf[ks] = *(const bf16x8*)(qptr + ks * 16 + 8 * hh);
;     ...
;     int kt = (q0 + 127) >> 6; if (kt > (L - 1) >> 6) kt = (L - 1) >> 6;
;     const int wqmax = q0 + w * 32 + 31;
;     const bf16_t* vsrc = aa.vt + ((size_t)(bh * 64 + lkey)) * LP + lsub * 8;
;     u32x4 rkA[KCH], rvA[2], rkB[KCH], rvB[2]; float rfA = 0.f, rfB = 0.f;
;     auto gload = [&](u32x4 (&rk)[KCH], u32x4 (&rv)[2], float& rf, int ktile) {
;       int kp = ktile * 64 + lkey; kp = kp < L ? kp : L - 1;
;       const size_t mk = (size_t)(b * L + kp);
;       const bf16_t* ks_ = aa.k + mk * D + hd * 64 + lsub * 8;
;       rk[0] = *(const u32x4*)ks_; __builtin_amdgcn_sched_barrier(0);
;       rk[1] = *(const u32x4*)(ks_ + 32); __builtin_amdgcn_sched_barrier(0);
;       if (MODE == 1) { rk[KCH - 1] = *(const u32x4*)(aa.kr + mk * 32 + lsub * 8); __builtin_amdgcn_sched_barrier(0); }
;       rv[0] = *(const u32x4*)(vsrc + ktile * 64); __builtin_amdgcn_sched_barrier(0);
;       rv[1] = *(const u32x4*)(vsrc + ktile * 64 + 32); __builtin_amdgcn_sched_barrier(0);
;       if (MODE == 2) { rf = aa.Fh[(size_t)bh * LP + ktile * 64 + (t & 63)]; __builtin_amdgcn_sched_barrier(0); }
;     };
;     auto lstore = [&](const u32x4 (&rk)[KCH], const u32x4 (&rv)[2], const float rf, int buf) {
;       bf16_t* kd = Kl + buf * 64 * KST + lkey * KST + lsub * 8;
;       *(u32x4*)kd = rk[0]; *(u32x4*)(kd + 32) = rk[1];
;       if (MODE == 1) *(u32x4*)(kd + 64) = rk[KCH - 1];
;       bf16_t* vd = Vl + buf * 64 * VST + lkey * VST + lsub * 8;
;       u32x2 lo, hi;
;       lo[0] = rv[0][0]; lo[1] = rv[0][1]; hi[0] = rv[0][2]; hi[1] = rv[0][3];
;       *(u32x2*)vd = lo; *(u32x2*)(vd + 4) = hi;
;       lo[0] = rv[1][0]; lo[1] = rv[1][1]; hi[0] = rv[1][2]; hi[1] = rv[1][3];
;       *(u32x2*)(vd + 32) = lo; *(u32x2*)(vd + 36) = hi;
;       if (MODE == 2 && t < 64) Fl[buf * 64 + t] = -rf * LOG2E;
;     };
.LBB0_1120:
	s_or_b64 exec, exec, s[4:5]
	s_waitcnt lgkmcnt(0)
	s_barrier
	ds_read_b64 v[0:1], v145 offset:36352
	s_waitcnt lgkmcnt(0)
	v_readfirstlane_b32 s1, v0
	s_cmp_lt_i32 s1, 0
	v_readfirstlane_b32 s33, v1
	s_cbranch_scc1 .LBB0_1140
	s_lshr_b32 s5, s1, 3
	s_mul_hi_u32 s6, s5, 0x3f03f04
	s_mulk_i32 s6, 0x41
	s_and_b32 s4, s1, 7
	s_sub_i32 s5, s5, s6
	s_mul_hi_u32 s1, s1, 0xfc0fc0fd
	s_lshr_b32 s6, s1, 6
	s_lshr_b32 s39, s1, 10
	s_lshl_b32 s1, s5, 7
	v_subrev_u32_e32 v2, s1, v134
	v_add_u32_e32 v122, v2, v123
	v_min_i32_e32 v0, 0x200f, v122
	s_mulk_i32 s39, 0x2010
	s_and_b32 s6, s6, 0x3fffff8
	v_add_u32_e32 v0, s39, v0
	s_or_b32 s4, s6, s4
	v_ashrrev_i32_e32 v1, 31, v0
	v_lshlrev_b64 v[0:1], 11, v[0:1]
	s_lshl_b32 s5, s4, 7
	v_lshl_add_u64 v[0:1], s[68:69], 0, v[0:1]
	s_and_b32 s18, s5, 0x780
	s_sub_i32 s1, 0x2040, s1
	s_waitcnt vmcnt(0)
	v_lshl_add_u64 v[124:125], v[0:1], 0, s[18:19]
	s_lshr_b32 s1, s1, 6
	v_lshl_add_u64 v[0:1], v[124:125], 0, v[144:145]
	s_min_u32 s1, s1, 0x80
	global_load_dwordx4 v[64:67], v[0:1], off
	global_load_dwordx4 v[68:71], v[0:1], off offset:32
	global_load_dwordx4 v[72:75], v[0:1], off offset:64
	global_load_dwordx4 v[76:79], v[0:1], off offset:96
	v_lshl_add_u32 v0, s4, 6, v115
	s_lshl_b32 s6, s1, 6
	v_mad_i64_i32 v[126:127], s[4:5], v0, s27, v[116:117]
	v_add_u32_e32 v0, s6, v115
	v_min_i32_e32 v0, 0x200f, v0
	v_add_u32_e32 v0, s39, v0
	v_ashrrev_i32_e32 v1, 31, v0
	v_readlane_b32 s8, v228, 23
	v_lshlrev_b64 v[0:1], 11, v[0:1]
	v_readlane_b32 s9, v228, 24
	v_mov_b32_e32 v121, v145
	s_nop 0
	v_lshl_add_u64 v[0:1], s[8:9], 0, v[0:1]
	v_lshl_add_u64 v[0:1], v[0:1], 0, s[18:19]
	v_lshl_add_u64 v[0:1], v[0:1], 0, v[120:121]
	global_load_dwordx4 v[80:83], v[0:1], off
	global_load_dwordx4 v[84:87], v[0:1], off offset:64
	s_lshl_b32 s4, s1, 7
	s_mov_b32 s5, s19
	v_lshl_add_u64 v[0:1], v[126:127], 0, s[4:5]
	global_load_dwordx4 v[88:91], v[0:1], off
	global_load_dwordx4 v[92:95], v[0:1], off offset:64
	s_sub_i32 s4, s6, 64
	v_add_u32_e32 v0, s4, v115
	v_min_i32_e32 v0, 0x200f, v0
	v_add_u32_e32 v0, s39, v0
	v_ashrrev_i32_e32 v1, 31, v0
	v_lshlrev_b64 v[0:1], 11, v[0:1]
	v_lshl_add_u64 v[0:1], s[8:9], 0, v[0:1]
	v_lshl_add_u64 v[0:1], v[0:1], 0, s[18:19]
	v_lshl_add_u64 v[0:1], v[0:1], 0, v[120:121]
	global_load_dwordx4 v[96:99], v[0:1], off
	global_load_dwordx4 v[100:103], v[0:1], off offset:64
	v_lshl_add_u64 v[0:1], s[4:5], 1, v[126:127]
	global_load_dwordx4 v[104:107], v[0:1], off
	global_load_dwordx4 v[108:111], v[0:1], off offset:64
	s_movk_i32 s4, 0x200f
	v_mov_b32_e32 v14, v145
	v_mov_b32_e32 v15, v145
	v_cmp_lt_i32_e64 s[50:51], s4, v122
	s_movk_i32 s4, 0x2010
	v_add_u32_e32 v140, 0x201f, v2
	v_mov_b32_e32 v0, v145
	v_mov_b32_e32 v1, v145
	v_mov_b32_e32 v2, v145
	v_mov_b32_e32 v3, v145
	v_mov_b32_e32 v4, v145
	v_mov_b32_e32 v5, v145
	v_mov_b32_e32 v6, v145
	v_mov_b32_e32 v7, v145
	v_mov_b32_e32 v8, v145
	v_mov_b32_e32 v9, v145
	v_mov_b32_e32 v10, v145
	v_mov_b32_e32 v11, v145
	v_mov_b32_e32 v12, v145
	v_mov_b32_e32 v13, v145
	v_mov_b64_e32 v[30:31], v[14:15]
	v_add_u32_e32 v121, 0x4800, v135
	v_add_u32_e32 v139, 0x4840, v135
	v_cmp_gt_i32_e64 s[48:49], s4, v122
	v_lshl_add_u64 v[128:129], v[118:119], 0, s[18:19]
	v_mov_b32_e32 v113, v122
	v_mov_b32_e32 v141, 0
	v_mov_b64_e32 v[28:29], v[12:13]
	v_mov_b64_e32 v[26:27], v[10:11]
	v_mov_b64_e32 v[24:25], v[8:9]
	v_mov_b64_e32 v[22:23], v[6:7]
	v_mov_b64_e32 v[20:21], v[4:5]
	v_mov_b64_e32 v[18:19], v[2:3]
	v_mov_b64_e32 v[16:17], v[0:1]
	s_waitcnt vmcnt(7)
	ds_write_b128 v112, v[80:83]
	s_waitcnt vmcnt(6)
	ds_write_b128 v112, v[84:87] offset:64
	s_waitcnt vmcnt(5)
	ds_write2_b64 v121, v[88:89], v[90:91] offset1:2
	s_waitcnt vmcnt(4)
	ds_write2_b64 v139, v[92:93], v[94:95] offset1:2
	s_branch .LBB0_1124

; #define MFMA32(a, b, c) __builtin_amdgcn_mfma_f32_32x32x16_bf16((a), (b), (c), 0, 0, 0)
; DI float fexp2(float x) { return __builtin_amdgcn_exp2f(x); }
; DI float flog2(float x) { return __builtin_amdgcn_logf(x); }
;     ...
;       { const int kpre = kt > 1 ? kt - 2 : 0; if (PAR == 0) gload(rkA, rvA, rfA, kpre); else gload(rkB, rvB, rfB, kpre); }
;       if (kt * 64 <= wqmax && dry < 2) {
;         const bf16_t* Kb = Kl + buf * 64 * KST; const bf16_t* Vb = Vl + buf * 64 * VST;
;         f32x16 s[2];
; #pragma unroll
;         for (int i = 0; i < 16; ++i) { s[0][i] = 0.f; s[1][i] = 0.f; }
;         if (MODE == 0) {
; #pragma unroll
;           for (int ks = 0; ks < NKS; ++ks) {
;             const bf16x8 a0 = *(const bf16x8*)(Kb + r * KST + ks * 16 + 8 * hh);
;             const bf16x8 a1 = *(const bf16x8*)(Kb + (32 + r) * KST + ks * 16 + 8 * hh);
;             s[0] = MFMA32(a0, qf[ks], s[0]);
;             s[1] = MFMA32(a1, qf[ks], s[1]);
;           }
;     ...
;         if (MODE == 0) {
;           float Gs[8]; float lk[2][16];
; #pragma unroll
;           for (int j = 0; j < 2; ++j)
; #pragma unroll
;             for (int g = 0; g < 4; ++g) {
;               float gsum = 0.f;
; #pragma unroll
;               for (int e = 0; e < 4; ++e) {
;                 const int i = 4 * g + e;
;                 const float z = s[j][i] * 0.125f;
;                 const float sp = fmaxf(z, 0.f) + 0.69314718f * flog2(1.f + fexp2(-fabsf(z) * LOG2E));
;                 const bool valid = (kbase + j * 32 + 8 * g + e) < posq;
;                 const float l = valid ? -sp : 0.f;
;                 lk[j][i] = l; gsum += l;
;                 s[j][i] = z - sp;
;               }
;               Gs[j * 4 + g] = gsum;
;             }
.LBB0_1128:
	s_max_i32 s4, s1, 2
	s_lshl_b32 s4, s4, 6
	s_addk_i32 s4, 0xff80
	v_add_u32_e32 v32, s4, v115
	v_min_i32_e32 v32, 0x200f, v32
	v_add_u32_e32 v32, s39, v32
	v_ashrrev_i32_e32 v33, 31, v32
	v_lshlrev_b64 v[32:33], 11, v[32:33]
	v_lshl_add_u64 v[32:33], v[128:129], 0, v[32:33]
	global_load_dwordx4 v[80:83], v[32:33], off
	global_load_dwordx4 v[84:87], v[32:33], off offset:64
	s_ashr_i32 s5, s4, 31
	v_lshl_add_u64 v[32:33], s[4:5], 1, v[126:127]
	global_load_dwordx4 v[88:91], v[32:33], off
	global_load_dwordx4 v[92:95], v[32:33], off offset:64
	s_lshl_b32 s4, s1, 6
	v_cmp_le_i32_e32 vcc, s4, v140
	s_and_saveexec_b64 s[24:25], vcc
	s_cbranch_execz .LBB0_1130
	ds_read_b128 v[32:35], v137
	ds_read_b128 v[130:133], v137 offset:32
	ds_read_b128 v[48:51], v137 offset:4608
	ds_read_b128 v[152:155], v137 offset:4640
	v_or_b32_e32 v211, s4, v114
	v_cmp_lt_i32_e64 s[94:95], v211, v122
	s_waitcnt lgkmcnt(3)
	v_mfma_f32_32x32x16_bf16 v[32:47], v[32:35], v[64:67], 0
	s_waitcnt lgkmcnt(2)
	v_mfma_f32_32x32x16_bf16 v[32:47], v[130:133], v[68:71], v[32:47]
	ds_read_b128 v[130:133], v137 offset:64
	ds_read_b128 v[156:159], v137 offset:96
	ds_read_b128 v[160:163], v137 offset:4672
	ds_read_b128 v[164:167], v137 offset:4704
	s_waitcnt lgkmcnt(3)
	v_mfma_f32_32x32x16_bf16 v[32:47], v[130:133], v[72:75], v[32:47]
	s_waitcnt lgkmcnt(2)
	v_mfma_f32_32x32x16_bf16 v[32:47], v[156:159], v[76:79], v[32:47]
	v_mfma_f32_32x32x16_bf16 v[48:63], v[48:51], v[64:67], 0
	s_nop 10
	v_mul_f32_e32 v131, 0x3e000000, v33
	v_mul_f32_e32 v130, 0x3e000000, v32
	v_mul_f32_e32 v142, 0x3e000000, v36
	v_max_f32_e32 v157, 0, v131
	v_mul_f32_e64 v131, |v131|, s38
	v_mul_f32_e64 v156, |v130|, s38
	v_max_f32_e32 v159, 0, v142
	v_mul_f32_e64 v142, |v142|, s38
	v_exp_f32_e32 v131, v131
	v_exp_f32_e32 v156, v156
	v_exp_f32_e32 v142, v142
	v_mfma_f32_32x32x16_bf16 v[48:63], v[152:155], v[68:71], v[48:63]
	v_add_f32_e32 v131, 1.0, v131
	v_add_f32_e32 v152, 1.0, v156
	v_add_f32_e32 v142, 1.0, v142
	v_log_f32_e32 v131, v131
	v_log_f32_e32 v152, v152
	v_log_f32_e32 v142, v142
	v_max_f32_e32 v143, 0, v130
	v_fmac_f32_e32 v157, 0x3f317218, v131
	v_fmac_f32_e32 v143, 0x3f317218, v152
	v_fma_f32 v152, v33, s3, -v157
	v_fmac_f32_e32 v159, 0x3f317218, v142
	v_mul_f32_e32 v33, 0x3e000000, v38
	v_fma_f32 v142, v36, s3, -v159
	v_mul_f32_e64 v36, |v33|, s38
	v_mul_f32_e32 v133, 0x3e000000, v35
	v_exp_f32_e32 v36, v36
	v_max_f32_e32 v158, 0, v133
	v_mul_f32_e64 v133, |v133|, s38
	v_mul_f32_e32 v150, 0x3e000000, v37
	v_exp_f32_e32 v133, v133
	v_mul_f32_e64 v168, |v150|, s38
	v_exp_f32_e32 v168, v168
	v_add_f32_e32 v36, 1.0, v36
	v_log_f32_e32 v36, v36
	v_add_f32_e32 v133, 1.0, v133
	v_log_f32_e32 v133, v133
	v_sub_f32_e32 v169, 0, v143
	v_fma_f32 v143, v32, s3, -v143
	s_waitcnt lgkmcnt(1)
	v_mfma_f32_32x32x16_bf16 v[48:63], v[160:163], v[72:75], v[48:63]
	v_add_f32_e32 v32, 1.0, v168
	v_max_f32_e32 v160, 0, v33
	v_mul_f32_e32 v33, 0x3e000000, v40
	v_log_f32_e32 v32, v32
	v_fmac_f32_e32 v160, 0x3f317218, v36
	v_mul_f32_e64 v36, |v33|, s38
	v_exp_f32_e32 v36, v36
	v_fmac_f32_e32 v158, 0x3f317218, v133
	v_fma_f32 v155, v35, s3, -v158
	v_sub_f32_e32 v35, 0, v159
	v_max_f32_e32 v159, 0, v150
	v_fmac_f32_e32 v159, 0x3f317218, v32
	v_mul_f32_e32 v32, 0x3e000000, v39
	v_fma_f32 v150, v37, s3, -v159
	v_mul_f32_e64 v37, |v32|, s38
	v_max_f32_e32 v131, 0, v32
	v_add_f32_e32 v32, 1.0, v36
	v_exp_f32_e32 v37, v37
	v_log_f32_e32 v32, v32
	v_max_f32_e32 v33, 0, v33
	v_fma_f32 v154, v38, s3, -v160
	v_add_f32_e32 v36, 1.0, v37
	v_fmac_f32_e32 v33, 0x3f317218, v32
	v_mul_f32_e32 v32, 0x3e000000, v41
	v_log_f32_e32 v133, v36
	v_mul_f32_e64 v36, |v32|, s38
	v_exp_f32_e32 v36, v36
	v_sub_f32_e32 v161, 0, v33
	v_fma_f32 v153, v40, s3, -v33
	v_mul_f32_e32 v33, 0x3e000000, v42
	v_max_f32_e32 v38, 0, v32
	v_add_f32_e32 v32, 1.0, v36
	v_mul_f32_e64 v36, |v33|, s38
	v_log_f32_e32 v32, v32
	v_exp_f32_e32 v36, v36
	v_mul_f32_e32 v40, 0x3e000000, v44
	s_waitcnt lgkmcnt(0)
	v_mfma_f32_32x32x16_bf16 v[48:63], v[164:167], v[76:79], v[48:63]
	v_fmac_f32_e32 v38, 0x3f317218, v32
	v_max_f32_e32 v32, 0, v33
	v_add_f32_e32 v33, 1.0, v36
	v_log_f32_e32 v36, v33
	v_mul_f32_e32 v33, 0x3e000000, v43
	v_mul_f32_e64 v37, |v33|, s38
	v_fma_f32 v156, v41, s3, -v38
	v_exp_f32_e32 v37, v37
	v_mul_f32_e64 v41, |v40|, s38
	v_exp_f32_e32 v41, v41
	v_max_f32_e32 v162, 0, v33
	v_add_f32_e32 v37, 1.0, v37
	v_log_f32_e32 v37, v37
	v_add_f32_e32 v33, 1.0, v41
	v_log_f32_e32 v33, v33
	v_mul_f32_e32 v132, 0x3e000000, v34
	v_fmac_f32_e32 v162, 0x3f317218, v37
	v_max_f32_e32 v37, 0, v40
	v_fmac_f32_e32 v37, 0x3f317218, v33
	v_mul_f32_e32 v33, 0x3e000000, v45
	v_fma_f32 v164, v43, s3, -v162
	v_sub_f32_e32 v163, 0, v37
	v_fma_f32 v43, v44, s3, -v37
	v_mul_f32_e64 v37, |v33|, s38
	v_exp_f32_e32 v37, v37
	v_mul_f32_e32 v40, 0x3e000000, v46
	v_mul_f32_e64 v41, |v40|, s38
	v_exp_f32_e32 v41, v41
	v_add_f32_e32 v37, 1.0, v37
	v_log_f32_e32 v37, v37
	v_max_f32_e32 v165, 0, v33
	v_add_f32_e32 v33, 1.0, v41
	v_log_f32_e32 v33, v33
	v_max_f32_e32 v167, 0, v40
	v_mul_f32_e32 v40, 0x3e000000, v48
	v_fmac_f32_e32 v165, 0x3f317218, v37
	v_mul_f32_e64 v37, |v40|, s38
	v_exp_f32_e32 v37, v37
	v_fmac_f32_e32 v167, 0x3f317218, v33
	v_mul_f32_e32 v33, 0x3e000000, v47
	v_mul_f32_e64 v41, |v33|, s38
	v_exp_f32_e32 v41, v41
	v_add_f32_e32 v37, 1.0, v37
	v_log_f32_e32 v44, v37
	v_max_f32_e32 v40, 0, v40
	v_add_f32_e32 v37, 1.0, v41
	v_mul_f32_e32 v41, 0x3e000000, v49
	v_fmac_f32_e32 v40, 0x3f317218, v44
	v_mul_f32_e64 v44, |v41|, s38
	v_exp_f32_e32 v44, v44
	v_max_f32_e32 v187, 0, v41
	v_mul_f32_e32 v41, 0x3e000000, v50
	v_sub_f32_e32 v170, 0, v40
	v_fma_f32 v171, v48, s3, -v40
; DI float fexp2(float x) { return __builtin_amdgcn_exp2f(x); }
; DI float flog2(float x) { return __builtin_amdgcn_logf(x); }
;     ...
;         if (MODE == 0) {
;           float Gs[8]; float lk[2][16];
; #pragma unroll
;           for (int j = 0; j < 2; ++j)
; #pragma unroll
;             for (int g = 0; g < 4; ++g) {
;               float gsum = 0.f;
; #pragma unroll
;               for (int e = 0; e < 4; ++e) {
;                 const int i = 4 * g + e;
;                 const float z = s[j][i] * 0.125f;
;                 const float sp = fmaxf(z, 0.f) + 0.69314718f * flog2(1.f + fexp2(-fabsf(z) * LOG2E));
;                 const bool valid = (kbase + j * 32 + 8 * g + e) < posq;
;                 const float l = valid ? -sp : 0.f;
;                 lk[j][i] = l; gsum += l;
;                 s[j][i] = z - sp;
;               }
;               Gs[j * 4 + g] = gsum;
;             }
;           float inc[9]; float run = 0.f; inc[8] = 0.f;
; #pragma unroll
;           for (int q = 7; q >= 0; --q) { run += Gs[q]; inc[q] = run; }
;           float recv[8];
; #pragma unroll
;           for (int q = 0; q < 8; ++q) recv[q] = __shfl_xor(inc[q + 1] + (hh ? Gs[q] : 0.f), 32);
;           const float ptot = __shfl_xor(run, 32);
	v_add_f32_e32 v40, 1.0, v44
	v_mul_f32_e64 v44, |v41|, s38
	v_log_f32_e32 v40, v40
	v_exp_f32_e32 v44, v44
	v_fma_f32 v166, v45, s3, -v165
	v_fma_f32 v168, v46, s3, -v167
	v_fmac_f32_e32 v187, 0x3f317218, v40
	v_max_f32_e32 v40, 0, v41
	v_add_f32_e32 v41, 1.0, v44
	v_log_f32_e32 v44, v41
	v_mul_f32_e32 v41, 0x3e000000, v51
	v_mul_f32_e64 v45, |v41|, s38
	v_exp_f32_e32 v45, v45
	v_mul_f32_e32 v46, 0x3e000000, v52
	v_mul_f32_e64 v48, |v46|, s38
	v_exp_f32_e32 v48, v48
	v_add_f32_e32 v45, 1.0, v45
	v_log_f32_e32 v45, v45
	v_max_f32_e32 v189, 0, v41
	v_add_f32_e32 v41, 1.0, v48
	v_log_f32_e32 v41, v41
	v_fmac_f32_e32 v189, 0x3f317218, v45
	v_max_f32_e32 v45, 0, v46
	v_mul_f32_e32 v46, 0x3e000000, v54
	v_mul_f32_e64 v48, |v46|, s38
	v_exp_f32_e32 v48, v48
	v_fmac_f32_e32 v45, 0x3f317218, v41
	v_mul_f32_e32 v41, 0x3e000000, v53
	v_max_f32_e32 v194, 0, v46
	v_mul_f32_e32 v46, 0x3e000000, v56
	v_fma_f32 v190, v51, s3, -v189
	v_sub_f32_e32 v51, 0, v45
	v_fma_f32 v191, v52, s3, -v45
	v_mul_f32_e64 v45, |v41|, s38
	v_max_f32_e32 v192, 0, v41
	v_add_f32_e32 v41, 1.0, v48
	v_mul_f32_e64 v48, |v46|, s38
	v_exp_f32_e32 v45, v45
	v_exp_f32_e32 v48, v48
	v_fma_f32 v188, v49, s3, -v187
	v_mul_f32_e32 v49, 0x3e000000, v57
	v_add_f32_e32 v45, 1.0, v45
	v_add_f32_e32 v48, 1.0, v48
	v_mul_f32_e64 v52, |v49|, s38
	v_log_f32_e32 v45, v45
	v_log_f32_e32 v48, v48
	v_exp_f32_e32 v52, v52
	v_max_f32_e32 v46, 0, v46
	v_fmac_f32_e32 v192, 0x3f317218, v45
	v_fmac_f32_e32 v46, 0x3f317218, v48
	v_add_f32_e32 v48, 1.0, v52
	v_mul_f32_e32 v52, 0x3e000000, v58
	v_fma_f32 v193, v53, s3, -v192
	v_log_f32_e32 v48, v48
	v_mul_f32_e64 v53, |v52|, s38
	v_exp_f32_e32 v53, v53
	v_max_f32_e32 v198, 0, v49
	v_fmac_f32_e32 v198, 0x3f317218, v48
	v_mul_f32_e32 v48, 0x3e000000, v59
	v_sub_f32_e32 v196, 0, v46
	v_fma_f32 v197, v56, s3, -v46
	v_add_f32_e32 v46, 1.0, v53
	v_mul_f32_e64 v49, |v48|, s38
	v_log_f32_e32 v46, v46
	v_exp_f32_e32 v49, v49
	v_max_f32_e32 v200, 0, v52
	v_max_f32_e32 v202, 0, v48
	v_fmac_f32_e32 v200, 0x3f317218, v46
	v_add_f32_e32 v46, 1.0, v49
	v_mul_f32_e32 v49, 0x3e000000, v60
	v_mul_f32_e64 v52, |v49|, s38
	v_log_f32_e32 v46, v46
	v_exp_f32_e32 v52, v52
	v_mul_f32_e32 v48, 0x3e000000, v61
	v_max_f32_e32 v49, 0, v49
	v_fmac_f32_e32 v202, 0x3f317218, v46
	v_add_f32_e32 v46, 1.0, v52
	v_mul_f32_e64 v52, |v48|, s38
	v_log_f32_e32 v46, v46
	v_exp_f32_e32 v52, v52
	v_max_f32_e32 v206, 0, v48
	v_max_f32_e32 v130, 0, v132
	v_fmac_f32_e32 v49, 0x3f317218, v46
	v_add_f32_e32 v46, 1.0, v52
	v_log_f32_e32 v46, v46
	v_sub_f32_e32 v204, 0, v49
	v_fma_f32 v205, v60, s3, -v49
	v_mul_f32_e32 v49, 0x3e000000, v63
	v_fmac_f32_e32 v206, 0x3f317218, v46
	v_mul_f32_e32 v46, 0x3e000000, v62
	v_mul_f32_e64 v48, |v46|, s38
	v_exp_f32_e32 v48, v48
	v_mul_f32_e64 v52, |v49|, s38
	v_mul_f32_e64 v132, |v132|, s38
	v_exp_f32_e32 v52, v52
	v_exp_f32_e32 v132, v132
	v_add_f32_e32 v48, 1.0, v48
	v_log_f32_e32 v48, v48
	v_max_f32_e32 v208, 0, v46
	v_add_f32_e32 v46, 1.0, v52
	v_add_f32_e32 v132, 1.0, v132
	v_log_f32_e32 v46, v46
	v_log_f32_e32 v132, v132
	v_fmac_f32_e32 v208, 0x3f317218, v48
	v_fma_f32 v209, v62, s3, -v208
	v_max_f32_e32 v62, 0, v49
	v_fmac_f32_e32 v62, 0x3f317218, v46
	v_or_b32_e32 v46, 1, v211
	v_cmp_lt_i32_e64 s[84:85], v46, v122
	v_pk_fma_f32 v[52:53], v[132:133], s[28:29], v[130:131] op_sel_hi:[1,0,1]
	v_log_f32_e32 v41, v41
	v_cndmask_b32_e64 v48, 0, -v157, s[84:85]
	v_fma_f32 v157, v34, s3, -v52
	v_or_b32_e32 v34, 3, v211
	v_cmp_lt_i32_e64 s[6:7], v34, v122
	v_or_b32_e32 v34, 8, v211
	v_cmp_lt_i32_e64 s[78:79], v34, v122
	v_fmac_f32_e32 v194, 0x3f317218, v41
	v_fma_f32 v199, v57, s3, -v198
	v_cndmask_b32_e64 v34, 0, v35, s[78:79]
	v_or_b32_e32 v35, 9, v211
	v_cmp_lt_i32_e64 s[80:81], v35, v122
	v_cndmask_b32_e64 v56, 0, v169, s[94:95]
	v_fma_f32 v195, v54, s3, -v194
	v_cndmask_b32_e64 v212, 0, -v159, s[80:81]
	v_add_f32_e32 v49, v212, v34
	v_or_b32_e32 v34, 10, v211
	v_cmp_lt_i32_e64 s[90:91], v34, v113
	v_or_b32_e32 v54, 2, v211
	v_cmp_lt_i32_e64 s[10:11], v54, v122
	v_cndmask_b32_e64 v57, 0, -v160, s[90:91]
	v_pk_add_f32 v[34:35], v[56:57], v[48:49]
	v_or_b32_e32 v49, 11, v211
	v_cmp_lt_i32_e64 s[4:5], v49, v113
	v_mul_f32_e32 v41, 0x3e000000, v55
	v_fma_f32 v201, v58, s3, -v200
	v_fma_f32 v203, v59, s3, -v202
	v_cndmask_b32_e64 v59, 0, -v53, s[4:5]
	v_cndmask_b32_e64 v58, 0, -v52, s[10:11]
	v_mul_f32_e64 v45, |v41|, s38
	v_fma_f32 v207, v61, s3, -v206
	v_pk_add_f32 v[60:61], v[58:59], v[34:35]
	v_or_b32_e32 v34, 17, v211
	v_or_b32_e32 v35, 25, v211
	v_exp_f32_e32 v45, v45
	v_fma_f32 v49, v39, s3, -v53
	v_cmp_lt_i32_e64 s[82:83], v34, v122
	v_or_b32_e32 v34, 19, v211
	v_cmp_lt_i32_e64 s[74:75], v35, v122
	v_or_b32_e32 v35, 40, v211
	v_or_b32_e32 v39, 41, v211
	v_cmp_lt_i32_e64 s[92:93], v34, v122
	v_or_b32_e32 v34, 24, v211
	v_cmp_lt_i32_e64 s[58:59], v35, v122
	v_cmp_lt_i32_e64 s[62:63], v39, v122
	v_cmp_lt_i32_e64 s[72:73], v34, v122
	v_cndmask_b32_e64 v56, 0, -v165, s[74:75]
	v_cndmask_b32_e64 v35, 0, v51, s[58:59]
	v_cndmask_b32_e64 v165, 0, -v192, s[62:63]
	v_cndmask_b32_e64 v34, 0, v163, s[72:73]
	v_add_f32_e32 v39, v165, v35
	v_or_b32_e32 v35, 48, v211
	v_or_b32_e32 v51, 49, v211
	v_add_f32_e32 v45, 1.0, v45
	v_add_f32_e32 v53, v56, v34
	v_or_b32_e32 v34, 33, v211
	v_cmp_lt_i32_e64 s[54:55], v35, v122
	v_cmp_lt_i32_e64 s[56:57], v51, v122
	v_or_b32_e32 v51, 50, v211
	v_log_f32_e32 v45, v45
	v_cmp_lt_i32_e64 s[70:71], v34, v122
	v_or_b32_e32 v34, 35, v211
	v_cndmask_b32_e64 v35, 0, v196, s[54:55]
	v_cndmask_b32_e64 v169, 0, -v198, s[56:57]
	v_cmp_lt_i32_e64 s[66:67], v51, v122
	v_or_b32_e32 v51, 51, v211
	v_cndmask_b32_e64 v52, 0, -v38, s[82:83]
; DI float fexp2(float x) { return __builtin_amdgcn_exp2f(x); }
;     ...
;           float inc[9]; float run = 0.f; inc[8] = 0.f;
; #pragma unroll
;           for (int q = 7; q >= 0; --q) { run += Gs[q]; inc[q] = run; }
;           float recv[8];
; #pragma unroll
;           for (int q = 0; q < 8; ++q) recv[q] = __shfl_xor(inc[q + 1] + (hh ? Gs[q] : 0.f), 32);
;           const float ptot = __shfl_xor(run, 32);
; #pragma unroll
;           for (int j = 0; j < 2; ++j)
; #pragma unroll
;             for (int g = 0; g < 4; ++g) {
;               const int q = j * 4 + g;
;               float later = Rrun + inc[q + 1] + recv[q];
; #pragma unroll
;               for (int e = 3; e >= 0; --e) {
;                 const int i = 4 * g + e;
;                 const bool valid = (kbase + j * 32 + 8 * g + e) < posq;
;                 const float a = valid ? fexp2((s[j][i] + later) * LOG2E) : 0.f;
;                 later += lk[j][i];
;                 s[j][i] = a;
;               }
;             }
	v_cndmask_b32_e64 v38, 0, -v187, s[70:71]
	v_cmp_lt_i32_e64 s[76:77], v34, v122
	v_add_f32_e32 v35, v169, v35
	v_cndmask_b32_e64 v187, 0, -v200, s[66:67]
	v_cmp_lt_i32_e64 s[68:69], v51, v122
	v_cndmask_b32_e64 v34, 0, -v189, s[76:77]
	v_add_f32_e32 v35, v187, v35
	v_cndmask_b32_e64 v189, 0, -v202, s[68:69]
	v_max_f32_e32 v41, 0, v41
	v_add_f32_e32 v192, v189, v35
	v_or_b32_e32 v35, 56, v211
	v_cmp_lt_i32_e64 s[40:41], v35, v122
	v_pk_fma_f32 v[40:41], v[44:45], s[28:29], v[40:41] op_sel_hi:[1,0,1]
	v_log_f32_e32 v37, v37
	v_cndmask_b32_e64 v35, 0, v204, s[40:41]
	v_or_b32_e32 v51, 57, v211
	v_fma_f32 v204, v50, s3, -v40
	v_or_b32_e32 v44, 42, v211
	v_or_b32_e32 v50, 32, v211
	v_cmp_lt_i32_e64 s[52:53], v51, v122
	v_or_b32_e32 v51, 58, v211
	v_cmp_lt_i32_e64 s[86:87], v44, v113
	v_cmp_lt_i32_e64 s[88:89], v50, v122
	v_cmp_lt_i32_e64 s[60:61], v51, v122
	v_or_b32_e32 v51, 59, v211
	v_cndmask_b32_e64 v45, 0, -v194, s[86:87]
	v_cndmask_b32_e64 v44, 0, v170, s[88:89]
	v_max_f32_e32 v33, 0, v33
	v_cndmask_b32_e64 v196, 0, -v206, s[52:53]
	v_cmp_lt_i32_e64 s[64:65], v51, v122
	v_pk_add_f32 v[50:51], v[44:45], v[38:39]
	v_or_b32_e32 v44, 34, v211
	v_add_f32_e32 v35, v196, v35
	v_cndmask_b32_e64 v198, 0, -v208, s[60:61]
	v_or_b32_e32 v39, 43, v211
	v_cmp_lt_i32_e64 s[8:9], v44, v122
	v_pk_fma_f32 v[32:33], v[36:37], s[28:29], v[32:33] op_sel_hi:[1,0,1]
	v_or_b32_e32 v36, 26, v211
	v_or_b32_e32 v44, 16, v211
	v_add_f32_e32 v35, v198, v35
	v_cndmask_b32_e64 v200, 0, -v62, s[64:65]
	v_cmp_lt_i32_e64 s[96:97], v39, v113
	v_cmp_lt_i32_e64 s[12:13], v36, v113
	v_cmp_lt_i32_e64 s[14:15], v44, v122
	v_add_f32_e32 v202, v200, v35
	v_fma_f32 v206, v55, s3, -v41
	v_cndmask_b32_e64 v41, 0, -v41, s[96:97]
	v_cndmask_b32_e64 v40, 0, -v40, s[8:9]
	v_cndmask_b32_e64 v37, 0, -v167, s[12:13]
	v_cndmask_b32_e64 v36, 0, v161, s[14:15]
	v_add_f32_e32 v35, v202, v192
	v_pk_add_f32 v[50:51], v[40:41], v[50:51]
	v_pk_add_f32 v[132:133], v[36:37], v[52:53]
	v_or_b32_e32 v36, 27, v211
	v_or_b32_e32 v44, 18, v211
	v_fma_f32 v210, v63, s3, -v62
	v_pk_add_f32 v[62:63], v[34:35], v[50:51]
	v_cmp_lt_i32_e64 s[16:17], v36, v113
	v_cmp_lt_i32_e64 s[20:21], v44, v122
	v_pk_add_f32 v[130:131], v[62:63], v[62:63] op_sel:[0,1] op_sel_hi:[1,0]
	v_fma_f32 v39, v42, s3, -v32
	v_fma_f32 v42, v47, s3, -v33
	v_cndmask_b32_e64 v33, 0, -v33, s[16:17]
	v_cndmask_b32_e64 v32, 0, -v32, s[20:21]
	v_cndmask_b32_e64 v54, 0, -v162, s[92:93]
	v_pk_add_f32 v[132:133], v[32:33], v[132:133]
	v_mov_b32_e32 v55, v130
	v_cndmask_b32_e64 v46, 0, -v158, s[6:7]
	v_pk_add_f32 v[158:159], v[54:55], v[132:133]
	v_and_b32_e32 v44, 64, v182
	v_pk_add_f32 v[160:161], v[158:159], v[158:159] op_sel:[0,1] op_sel_hi:[1,0]
	v_xor_b32_e32 v36, 32, v182
	v_mov_b32_e32 v47, v160
	v_add_u32_e32 v44, 64, v44
	v_pk_add_f32 v[162:163], v[46:47], v[60:61]
	v_cmp_lt_i32_e32 vcc, v36, v44
	v_cndmask_b32_e64 v44, v162, 0, s[46:47]
	v_add_f32_e32 v44, v44, v163
	v_cndmask_b32_e32 v36, v182, v36, vcc
	v_lshlrev_b32_e32 v36, 2, v36
	ds_bpermute_b32 v44, v36, v44
	v_add_f32_e32 v131, v141, v163
	v_cndmask_b32_e64 v47, v61, 0, s[46:47]
	v_cndmask_b32_e64 v53, v158, 0, s[46:47]
	v_cndmask_b32_e64 v55, v133, 0, s[46:47]
	s_waitcnt lgkmcnt(0)
	v_add_f32_e32 v44, v131, v44
	v_cndmask_b32_e64 v60, v62, 0, s[46:47]
	v_cndmask_b32_e64 v51, v51, 0, s[46:47]
	v_cndmask_b32_e64 v61, v192, 0, s[46:47]
	v_add_f32_e32 v131, v155, v44
	v_add_f32_e32 v44, v46, v44
	v_add_f32_e32 v50, v162, v163
	v_add_f32_e32 v47, v47, v160
	v_add_f32_e32 v53, v53, v159
	v_add_f32_e32 v55, v55, v130
	v_add_f32_e32 v60, v60, v63
	v_add_f32_e32 v51, v35, v51
	v_add_f32_e32 v61, v202, v61
	v_cndmask_b32_e64 v62, v202, 0, s[46:47]
	v_add_f32_e32 v46, v157, v44
	ds_bpermute_b32 v47, v36, v47
	ds_bpermute_b32 v53, v36, v53
	ds_bpermute_b32 v55, v36, v55
	ds_bpermute_b32 v60, v36, v60
	ds_bpermute_b32 v51, v36, v51
	ds_bpermute_b32 v61, v36, v61
	v_mul_f32_e32 v46, 0x3fb8aa3b, v46
	ds_bpermute_b32 v62, v36, v62
	ds_bpermute_b32 v132, v36, v50
	v_add_f32_e32 v36, v58, v44
	v_exp_f32_e32 v46, v46
	v_add_f32_e32 v44, v152, v36
	v_add_f32_e32 v36, v48, v36
	v_add_f32_e32 v36, v143, v36
	v_mul_f32_e32 v36, 0x3fb8aa3b, v36
	v_mul_f32_e32 v44, 0x3fb8aa3b, v44
	v_exp_f32_e32 v36, v36
	v_cndmask_b32_e64 v133, 0, v46, s[10:11]
	v_exp_f32_e32 v44, v44
	v_add_f32_e32 v46, v141, v160
	s_waitcnt lgkmcnt(7)
	v_add_f32_e32 v46, v46, v47
	v_add_f32_e32 v47, v49, v46
	v_add_f32_e32 v46, v59, v46
	v_mul_f32_e32 v47, 0x3fb8aa3b, v47
	v_cndmask_b32_e64 v58, 0, v36, s[94:95]
	v_add_f32_e32 v36, v57, v46
	v_exp_f32_e32 v47, v47
	v_cndmask_b32_e64 v49, 0, v44, s[84:85]
	v_add_f32_e32 v44, v150, v36
	v_add_f32_e32 v36, v212, v36
	v_add_f32_e32 v36, v142, v36
	v_add_f32_e32 v48, v154, v46
	v_mul_f32_e32 v36, 0x3fb8aa3b, v36
	v_add_f32_e32 v46, v141, v159
	v_exp_f32_e32 v36, v36
	s_waitcnt lgkmcnt(6)
	v_add_f32_e32 v46, v46, v53
	v_cndmask_b32_e64 v59, 0, v47, s[4:5]
	v_add_f32_e32 v47, v164, v46
	v_add_f32_e32 v46, v54, v46
	v_add_f32_e32 v39, v39, v46
	v_mul_f32_e32 v39, 0x3fb8aa3b, v39
	v_add_f32_e32 v32, v32, v46
	v_exp_f32_e32 v39, v39
	v_cndmask_b32_e64 v54, 0, v36, s[78:79]
	v_add_f32_e32 v36, v156, v32
	v_add_f32_e32 v32, v52, v32
	v_add_f32_e32 v32, v153, v32
	v_mul_f32_e32 v32, 0x3fb8aa3b, v32
	v_exp_f32_e32 v32, v32
	v_cndmask_b32_e64 v142, 0, v39, s[20:21]
	v_add_f32_e32 v39, v141, v130
	s_waitcnt lgkmcnt(5)
	v_add_f32_e32 v39, v39, v55
	v_add_f32_e32 v33, v33, v39
	v_mul_f32_e32 v36, 0x3fb8aa3b, v36
	v_cndmask_b32_e64 v55, 0, v32, s[14:15]
	v_add_f32_e32 v32, v37, v33
	v_exp_f32_e32 v36, v36
	v_add_f32_e32 v42, v42, v39
	v_add_f32_e32 v39, v168, v33
	v_add_f32_e32 v33, v166, v32
	v_add_f32_e32 v32, v56, v32
	v_add_f32_e32 v32, v43, v32
	v_mul_f32_e32 v32, 0x3fb8aa3b, v32
	v_mul_f32_e32 v33, 0x3fb8aa3b, v33
	v_exp_f32_e32 v32, v32
	v_cndmask_b32_e64 v52, 0, v36, s[82:83]
	v_exp_f32_e32 v33, v33
	v_add_f32_e32 v36, v141, v63
	s_waitcnt lgkmcnt(4)
; #define MFMA32(a, b, c) __builtin_amdgcn_mfma_f32_32x32x16_bf16((a), (b), (c), 0, 0, 0)
; DI float fexp2(float x) { return __builtin_amdgcn_exp2f(x); }
;     ...
;         auto ldv = [&](int j) {
; #pragma unroll
;           for (int st = 0; st < 2; ++st)
; #pragma unroll
;             for (int dt = 0; dt < 2; ++dt) {
;               const bf16_t* vp = Vb + (dt * 32 + r) * VST + j * 32 + 16 * st + 4 * hh;
;               const u32x2 lo = *(const u32x2*)vp, hi = *(const u32x2*)(vp + 8);
;               vfr[st][dt][0] = lo[0]; vfr[st][dt][1] = lo[1]; vfr[st][dt][2] = hi[0]; vfr[st][dt][3] = hi[1];
;             }
;           __builtin_amdgcn_sched_barrier(0);
;         };
;         auto pvm = [&](int j) {
; #pragma unroll
;           for (int st = 0; st < 2; ++st) {
;             u32x4 pp;
; #pragma unroll
;             for (int q = 0; q < 4; ++q) pp[q] = pk_bf16(s[j][8 * st + 2 * q], s[j][8 * st + 2 * q + 1]);
;             const bf16x8 pb = __builtin_bit_cast(bf16x8, pp);
; #pragma unroll
;             for (int dt = 0; dt < 2; ++dt) oacc[dt] = MFMA32(__builtin_bit_cast(bf16x8, vfr[st][dt]), pb, oacc[dt]);
;           }
;         };
;         auto pv = [&](int j) { ldv(j); pvm(j); };
;     ...
;           for (int j = 0; j < 2; ++j)
; #pragma unroll
;             for (int g = 0; g < 4; ++g) {
;               const int q = j * 4 + g;
;               float later = Rrun + inc[q + 1] + recv[q];
; #pragma unroll
;               for (int e = 3; e >= 0; --e) {
;                 const int i = 4 * g + e;
;                 const bool valid = (kbase + j * 32 + 8 * g + e) < posq;
;                 const float a = valid ? fexp2((s[j][i] + later) * LOG2E) : 0.f;
;                 later += lk[j][i];
;                 s[j][i] = a;
;               }
;             }
;           Rrun += run + ptot;
	v_add_f32_e32 v36, v36, v60
	v_add_f32_e32 v34, v34, v36
	v_cndmask_b32_e64 v60, 0, v32, s[72:73]
	v_add_f32_e32 v32, v40, v34
	v_cndmask_b32_e64 v56, 0, v33, s[74:75]
	v_add_f32_e32 v33, v188, v32
	v_add_f32_e32 v32, v38, v32
	v_add_f32_e32 v32, v171, v32
	v_mul_f32_e32 v32, 0x3fb8aa3b, v32
	v_add_f32_e32 v37, v190, v36
	v_add_f32_e32 v36, v204, v34
	v_mul_f32_e32 v33, 0x3fb8aa3b, v33
	v_exp_f32_e32 v32, v32
	v_mul_f32_e32 v36, 0x3fb8aa3b, v36
	v_exp_f32_e32 v33, v33
	v_add_f32_e32 v34, v141, v35
	v_exp_f32_e32 v36, v36
	s_waitcnt lgkmcnt(3)
	v_add_f32_e32 v34, v34, v51
	v_add_f32_e32 v35, v206, v34
	v_add_f32_e32 v34, v41, v34
	v_cndmask_b32_e64 v154, 0, v32, s[88:89]
	v_add_f32_e32 v32, v45, v34
	v_cndmask_b32_e64 v153, 0, v33, s[70:71]
	v_add_f32_e32 v33, v193, v32
	v_add_f32_e32 v32, v165, v32
	v_cndmask_b32_e64 v152, 0, v36, s[8:9]
	v_mul_f32_e32 v35, 0x3fb8aa3b, v35
	v_add_f32_e32 v36, v195, v34
	v_add_f32_e32 v32, v191, v32
	v_exp_f32_e32 v35, v35
	v_mul_f32_e32 v36, 0x3fb8aa3b, v36
	v_mul_f32_e32 v32, 0x3fb8aa3b, v32
	v_exp_f32_e32 v36, v36
	v_mul_f32_e32 v33, 0x3fb8aa3b, v33
	v_exp_f32_e32 v32, v32
	v_exp_f32_e32 v33, v33
	v_add_f32_e32 v34, v141, v202
	s_waitcnt lgkmcnt(2)
	v_add_f32_e32 v34, v34, v61
	v_cndmask_b32_e64 v155, 0, v35, s[96:97]
	v_add_f32_e32 v35, v203, v34
	v_add_f32_e32 v34, v189, v34
	v_cndmask_b32_e64 v156, 0, v36, s[86:87]
	v_mul_f32_e32 v35, 0x3fb8aa3b, v35
	v_add_f32_e32 v36, v201, v34
	v_cndmask_b32_e64 v157, 0, v32, s[58:59]
	v_add_f32_e32 v32, v187, v34
	v_exp_f32_e32 v35, v35
	v_mul_f32_e32 v36, 0x3fb8aa3b, v36
	v_cndmask_b32_e64 v61, 0, v33, s[62:63]
	v_add_f32_e32 v33, v199, v32
	v_add_f32_e32 v32, v169, v32
	v_exp_f32_e32 v36, v36
	v_add_f32_e32 v32, v197, v32
	v_mul_f32_e32 v32, 0x3fb8aa3b, v32
	v_add_f32_e32 v34, 0, v141
	v_mul_f32_e32 v33, 0x3fb8aa3b, v33
	v_exp_f32_e32 v32, v32
	s_waitcnt lgkmcnt(1)
	v_add_f32_e32 v34, v34, v62
	v_cndmask_b32_e64 v158, 0, v35, s[68:69]
	v_exp_f32_e32 v33, v33
	v_add_f32_e32 v35, v210, v34
	v_add_f32_e32 v34, v200, v34
	v_mul_f32_e32 v48, 0x3fb8aa3b, v48
	v_cndmask_b32_e64 v159, 0, v36, s[66:67]
	v_add_f32_e32 v36, v209, v34
	v_exp_f32_e32 v48, v48
	v_mul_f32_e32 v44, 0x3fb8aa3b, v44
	v_mul_f32_e32 v47, 0x3fb8aa3b, v47
	v_mul_f32_e32 v42, 0x3fb8aa3b, v42
	v_mul_f32_e32 v39, 0x3fb8aa3b, v39
	v_mul_f32_e32 v37, 0x3fb8aa3b, v37
	v_mul_f32_e32 v35, 0x3fb8aa3b, v35
	v_mul_f32_e32 v36, 0x3fb8aa3b, v36
	v_exp_f32_e32 v44, v44
	v_exp_f32_e32 v47, v47
	v_exp_f32_e32 v42, v42
	v_exp_f32_e32 v39, v39
	v_exp_f32_e32 v37, v37
	v_exp_f32_e32 v35, v35
	v_exp_f32_e32 v36, v36
	v_cndmask_b32_e64 v160, 0, v32, s[54:55]
	v_add_f32_e32 v32, v198, v34
	v_cndmask_b32_e64 v62, 0, v33, s[56:57]
	v_add_f32_e32 v33, v207, v32
	v_add_f32_e32 v32, v196, v32
	v_mul_f32_e32 v33, 0x3fb8aa3b, v33
	v_add_f32_e32 v32, v205, v32
	v_cndmask_b32_e64 v143, 0, v48, s[90:91]
	v_exp_f32_e32 v48, v33
	v_mul_f32_e32 v32, 0x3fb8aa3b, v32
	v_add_u32_e32 v163, 0x4800, v138
	v_add_u32_e32 v164, 0x5800, v138
	v_mul_f32_e32 v131, 0x3fb8aa3b, v131
	v_cndmask_b32_e64 v53, 0, v44, s[80:81]
	v_cndmask_b32_e64 v57, 0, v47, s[92:93]
	v_cndmask_b32_e64 v130, 0, v42, s[16:17]
	v_cndmask_b32_e64 v150, 0, v39, s[12:13]
	v_cndmask_b32_e64 v63, 0, v37, s[76:77]
	v_cndmask_b32_e64 v161, 0, v35, s[64:65]
	v_cndmask_b32_e64 v162, 0, v36, s[60:61]
	v_exp_f32_e32 v51, v32
	ds_read_b128 v[32:35], v138 offset:18432
	ds_read_b128 v[36:39], v138 offset:18464
	ds_read_b128 v[40:43], v138 offset:23040
	ds_read_b128 v[44:47], v138 offset:23072
	v_exp_f32_e32 v131, v131
	v_readlane_b32 s56, v223, 13
	v_cndmask_b32_e64 v165, 0, v48, s[52:53]
	s_waitcnt lgkmcnt(4)
	v_add_f32_e32 v48, v50, v132
	s_movk_i32 s73, 0x600
	s_mov_b32 s72, 0xfffffc0
	v_readlane_b32 s57, v223, 14
	v_readlane_b32 s58, v223, 15
	v_readlane_b32 s59, v223, 16
	v_readlane_b32 s60, v223, 17
	v_readlane_b32 s61, v223, 18
	v_readlane_b32 s62, v223, 19
	v_readlane_b32 s63, v223, 20
	v_readlane_b32 s64, v223, 21
	v_readlane_b32 s65, v223, 22
	v_readlane_b32 s66, v223, 23
	v_readlane_b32 s67, v223, 24
	v_readlane_b32 s68, v223, 25
	v_readlane_b32 s69, v223, 26
	v_readlane_b32 s70, v223, 27
	v_readlane_b32 s71, v223, 28
	v_add_f32_e32 v141, v141, v48
	v_cndmask_b32_e64 v131, 0, v131, s[6:7]
	v_cndmask_b32_e64 v166, 0, v51, s[40:41]
	v_cvt_pk_bf16_f32 v48, v58, v49
	v_cvt_pk_bf16_f32 v49, v133, v131
	v_cvt_pk_bf16_f32 v50, v54, v53
	v_cvt_pk_bf16_f32 v51, v143, v59
	s_waitcnt lgkmcnt(3)
	s_nop 0
	v_mfma_f32_32x32x16_bf16 v[16:31], v[32:35], v[48:51], v[16:31]
	v_cvt_pk_bf16_f32 v32, v55, v52
	v_cvt_pk_bf16_f32 v33, v142, v57
	v_cvt_pk_bf16_f32 v34, v60, v56
	v_cvt_pk_bf16_f32 v35, v150, v130
	s_waitcnt lgkmcnt(1)
	v_mfma_f32_32x32x16_bf16 v[0:15], v[40:43], v[48:51], v[0:15]
	v_mfma_f32_32x32x16_bf16 v[16:31], v[36:39], v[32:35], v[16:31]
	s_waitcnt lgkmcnt(0)
	v_mfma_f32_32x32x16_bf16 v[0:15], v[44:47], v[32:35], v[0:15]
	ds_read_b128 v[32:35], v138 offset:18496
	ds_read_b128 v[36:39], v138 offset:18528
	ds_read_b128 v[40:43], v138 offset:23104
	ds_read_b128 v[44:47], v138 offset:23136
	v_cvt_pk_bf16_f32 v48, v154, v153
	v_cvt_pk_bf16_f32 v49, v152, v63
	v_cvt_pk_bf16_f32 v50, v157, v61
	v_cvt_pk_bf16_f32 v51, v156, v155
	s_waitcnt lgkmcnt(3)
	s_nop 0
	v_mfma_f32_32x32x16_bf16 v[16:31], v[32:35], v[48:51], v[16:31]
	v_cvt_pk_bf16_f32 v32, v160, v62
	v_cvt_pk_bf16_f32 v33, v159, v158
	v_cvt_pk_bf16_f32 v34, v166, v165
	v_cvt_pk_bf16_f32 v35, v162, v161
	s_waitcnt lgkmcnt(1)
	v_mfma_f32_32x32x16_bf16 v[0:15], v[40:43], v[48:51], v[0:15]
	v_mfma_f32_32x32x16_bf16 v[16:31], v[36:39], v[32:35], v[16:31]
	s_waitcnt lgkmcnt(0)
	v_mfma_f32_32x32x16_bf16 v[0:15], v[44:47], v[32:35], v[0:15]
.LBB0_1130:
	s_or_b64 exec, exec, s[24:25]
	s_add_i32 s6, s1, -1
	v_add_u32_e32 v32, 0x9000, v135
	s_cmp_lt_i32 s1, 1
	s_waitcnt vmcnt(7)
	ds_write_b128 v112, v[96:99] offset:9216
	s_waitcnt vmcnt(6)
	ds_write_b128 v112, v[100:103] offset:9280
	s_waitcnt vmcnt(5)
	ds_write2_b64 v32, v[104:105], v[106:107] offset1:2
	v_add_u32_e32 v32, 0x9040, v135
	s_cselect_b64 s[4:5], -1, 0
	s_mov_b32 s1, s6
	s_waitcnt vmcnt(4)
	ds_write2_b64 v32, v[108:109], v[110:111] offset1:2
	s_xor_b64 s[4:5], s[4:5], -1
	s_andn2_b64 vcc, exec, s[4:5]
	s_mov_b64 s[4:5], -1
	s_cbranch_vccnz .LBB0_1122

; #define MFMA32(a, b, c) __builtin_amdgcn_mfma_f32_32x32x16_bf16((a), (b), (c), 0, 0, 0)
; DI float fexp2(float x) { return __builtin_amdgcn_exp2f(x); }
; DI float flog2(float x) { return __builtin_amdgcn_logf(x); }
;     ...
;       { const int kpre = kt > 1 ? kt - 2 : 0; if (PAR == 0) gload(rkA, rvA, rfA, kpre); else gload(rkB, rvB, rfB, kpre); }
;       if (kt * 64 <= wqmax && dry < 2) {
;         const bf16_t* Kb = Kl + buf * 64 * KST; const bf16_t* Vb = Vl + buf * 64 * VST;
;         f32x16 s[2];
; #pragma unroll
;         for (int i = 0; i < 16; ++i) { s[0][i] = 0.f; s[1][i] = 0.f; }
;         if (MODE == 0) {
; #pragma unroll
;           for (int ks = 0; ks < NKS; ++ks) {
;             const bf16x8 a0 = *(const bf16x8*)(Kb + r * KST + ks * 16 + 8 * hh);
;             const bf16x8 a1 = *(const bf16x8*)(Kb + (32 + r) * KST + ks * 16 + 8 * hh);
;             s[0] = MFMA32(a0, qf[ks], s[0]);
;             s[1] = MFMA32(a1, qf[ks], s[1]);
;           }
;     ...
;         if (MODE == 0) {
;           float Gs[8]; float lk[2][16];
; #pragma unroll
;           for (int j = 0; j < 2; ++j)
; #pragma unroll
;             for (int g = 0; g < 4; ++g) {
;               float gsum = 0.f;
; #pragma unroll
;               for (int e = 0; e < 4; ++e) {
;                 const int i = 4 * g + e;
;                 const float z = s[j][i] * 0.125f;
;                 const float sp = fmaxf(z, 0.f) + 0.69314718f * flog2(1.f + fexp2(-fabsf(z) * LOG2E));
;                 const bool valid = (kbase + j * 32 + 8 * g + e) < posq;
;                 const float l = valid ? -sp : 0.f;
;                 lk[j][i] = l; gsum += l;
;                 s[j][i] = z - sp;
;               }
;               Gs[j * 4 + g] = gsum;
;             }
.LBB0_1135:
	s_max_i32 s4, s1, 2
	s_lshl_b32 s4, s4, 6
	s_addk_i32 s4, 0xff80
	v_add_u32_e32 v32, s4, v115
	v_min_i32_e32 v32, 0x200f, v32
	v_add_u32_e32 v32, s39, v32
	v_ashrrev_i32_e32 v33, 31, v32
	v_lshlrev_b64 v[32:33], 11, v[32:33]
	v_lshl_add_u64 v[32:33], v[128:129], 0, v[32:33]
	global_load_dwordx4 v[96:99], v[32:33], off
	global_load_dwordx4 v[100:103], v[32:33], off offset:64
	s_ashr_i32 s5, s4, 31
	v_lshl_add_u64 v[32:33], s[4:5], 1, v[126:127]
	global_load_dwordx4 v[104:107], v[32:33], off
	global_load_dwordx4 v[108:111], v[32:33], off offset:64
	s_lshl_b32 s4, s1, 6
	v_cmp_le_i32_e32 vcc, s4, v140
	s_and_saveexec_b64 s[24:25], vcc
	s_cbranch_execz .LBB0_1137
	ds_read_b128 v[32:35], v137 offset:9216
	ds_read_b128 v[130:133], v137 offset:9248
	ds_read_b128 v[48:51], v137 offset:13824
	ds_read_b128 v[152:155], v137 offset:13856
	v_or_b32_e32 v211, s4, v114
	v_cmp_lt_i32_e64 s[94:95], v211, v122
	s_waitcnt lgkmcnt(3)
	v_mfma_f32_32x32x16_bf16 v[32:47], v[32:35], v[64:67], 0
	s_waitcnt lgkmcnt(2)
	v_mfma_f32_32x32x16_bf16 v[32:47], v[130:133], v[68:71], v[32:47]
	ds_read_b128 v[130:133], v137 offset:9280
	ds_read_b128 v[156:159], v137 offset:9312
	ds_read_b128 v[160:163], v137 offset:13888
	ds_read_b128 v[164:167], v137 offset:13920
	s_waitcnt lgkmcnt(3)
	v_mfma_f32_32x32x16_bf16 v[32:47], v[130:133], v[72:75], v[32:47]
	s_waitcnt lgkmcnt(2)
	v_mfma_f32_32x32x16_bf16 v[32:47], v[156:159], v[76:79], v[32:47]
	v_mfma_f32_32x32x16_bf16 v[48:63], v[48:51], v[64:67], 0
	s_nop 10
	v_mul_f32_e32 v131, 0x3e000000, v33
	v_mul_f32_e32 v130, 0x3e000000, v32
	v_mul_f32_e32 v142, 0x3e000000, v36
	v_max_f32_e32 v157, 0, v131
	v_mul_f32_e64 v131, |v131|, s38
	v_mul_f32_e64 v156, |v130|, s38
	v_max_f32_e32 v159, 0, v142
	v_mul_f32_e64 v142, |v142|, s38
	v_exp_f32_e32 v131, v131
	v_exp_f32_e32 v156, v156
	v_exp_f32_e32 v142, v142
	v_mfma_f32_32x32x16_bf16 v[48:63], v[152:155], v[68:71], v[48:63]
	v_add_f32_e32 v131, 1.0, v131
	v_add_f32_e32 v152, 1.0, v156
	v_add_f32_e32 v142, 1.0, v142
	v_log_f32_e32 v131, v131
	v_log_f32_e32 v152, v152
	v_log_f32_e32 v142, v142
	v_max_f32_e32 v143, 0, v130
	v_fmac_f32_e32 v157, 0x3f317218, v131
	v_fmac_f32_e32 v143, 0x3f317218, v152
	v_fma_f32 v152, v33, s3, -v157
	v_fmac_f32_e32 v159, 0x3f317218, v142
	v_mul_f32_e32 v33, 0x3e000000, v38
	v_fma_f32 v142, v36, s3, -v159
	v_mul_f32_e64 v36, |v33|, s38
	v_mul_f32_e32 v133, 0x3e000000, v35
	v_exp_f32_e32 v36, v36
	v_max_f32_e32 v158, 0, v133
	v_mul_f32_e64 v133, |v133|, s38
	v_mul_f32_e32 v150, 0x3e000000, v37
	v_exp_f32_e32 v133, v133
	v_mul_f32_e64 v168, |v150|, s38
	v_exp_f32_e32 v168, v168
	v_add_f32_e32 v36, 1.0, v36
	v_log_f32_e32 v36, v36
	v_add_f32_e32 v133, 1.0, v133
	v_log_f32_e32 v133, v133
	v_sub_f32_e32 v169, 0, v143
	v_fma_f32 v143, v32, s3, -v143
	s_waitcnt lgkmcnt(1)
	v_mfma_f32_32x32x16_bf16 v[48:63], v[160:163], v[72:75], v[48:63]
	v_add_f32_e32 v32, 1.0, v168
	v_max_f32_e32 v160, 0, v33
	v_mul_f32_e32 v33, 0x3e000000, v40
	v_log_f32_e32 v32, v32
	v_fmac_f32_e32 v160, 0x3f317218, v36
	v_mul_f32_e64 v36, |v33|, s38
	v_exp_f32_e32 v36, v36
	v_fmac_f32_e32 v158, 0x3f317218, v133
	v_fma_f32 v155, v35, s3, -v158
	v_sub_f32_e32 v35, 0, v159
	v_max_f32_e32 v159, 0, v150
	v_fmac_f32_e32 v159, 0x3f317218, v32
	v_mul_f32_e32 v32, 0x3e000000, v39
	v_fma_f32 v150, v37, s3, -v159
	v_mul_f32_e64 v37, |v32|, s38
	v_max_f32_e32 v131, 0, v32
	v_add_f32_e32 v32, 1.0, v36
	v_exp_f32_e32 v37, v37
	v_log_f32_e32 v32, v32
	v_max_f32_e32 v33, 0, v33
	v_fma_f32 v154, v38, s3, -v160
	v_add_f32_e32 v36, 1.0, v37
	v_fmac_f32_e32 v33, 0x3f317218, v32
	v_mul_f32_e32 v32, 0x3e000000, v41
	v_log_f32_e32 v133, v36
	v_mul_f32_e64 v36, |v32|, s38
	v_exp_f32_e32 v36, v36
	v_sub_f32_e32 v161, 0, v33
	v_fma_f32 v153, v40, s3, -v33
	v_mul_f32_e32 v33, 0x3e000000, v42
	v_max_f32_e32 v38, 0, v32
	v_add_f32_e32 v32, 1.0, v36
	v_mul_f32_e64 v36, |v33|, s38
	v_log_f32_e32 v32, v32
	v_exp_f32_e32 v36, v36
	v_mul_f32_e32 v40, 0x3e000000, v44
	s_waitcnt lgkmcnt(0)
	v_mfma_f32_32x32x16_bf16 v[48:63], v[164:167], v[76:79], v[48:63]
	v_fmac_f32_e32 v38, 0x3f317218, v32
	v_max_f32_e32 v32, 0, v33
	v_add_f32_e32 v33, 1.0, v36
	v_log_f32_e32 v36, v33
	v_mul_f32_e32 v33, 0x3e000000, v43
	v_mul_f32_e64 v37, |v33|, s38
	v_fma_f32 v156, v41, s3, -v38
	v_exp_f32_e32 v37, v37
	v_mul_f32_e64 v41, |v40|, s38
	v_exp_f32_e32 v41, v41
	v_max_f32_e32 v162, 0, v33
	v_add_f32_e32 v37, 1.0, v37
	v_log_f32_e32 v37, v37
	v_add_f32_e32 v33, 1.0, v41
	v_log_f32_e32 v33, v33
	v_mul_f32_e32 v132, 0x3e000000, v34
	v_fmac_f32_e32 v162, 0x3f317218, v37
	v_max_f32_e32 v37, 0, v40
	v_fmac_f32_e32 v37, 0x3f317218, v33
	v_mul_f32_e32 v33, 0x3e000000, v45
	v_fma_f32 v164, v43, s3, -v162
	v_sub_f32_e32 v163, 0, v37
	v_fma_f32 v43, v44, s3, -v37
	v_mul_f32_e64 v37, |v33|, s38
	v_exp_f32_e32 v37, v37
	v_mul_f32_e32 v40, 0x3e000000, v46
	v_mul_f32_e64 v41, |v40|, s38
	v_exp_f32_e32 v41, v41
	v_add_f32_e32 v37, 1.0, v37
	v_log_f32_e32 v37, v37
	v_max_f32_e32 v165, 0, v33
	v_add_f32_e32 v33, 1.0, v41
	v_log_f32_e32 v33, v33
	v_max_f32_e32 v167, 0, v40
	v_mul_f32_e32 v40, 0x3e000000, v48
	v_fmac_f32_e32 v165, 0x3f317218, v37
	v_mul_f32_e64 v37, |v40|, s38
	v_exp_f32_e32 v37, v37
	v_fmac_f32_e32 v167, 0x3f317218, v33
	v_mul_f32_e32 v33, 0x3e000000, v47
	v_mul_f32_e64 v41, |v33|, s38
	v_exp_f32_e32 v41, v41
	v_add_f32_e32 v37, 1.0, v37
	v_log_f32_e32 v44, v37
	v_max_f32_e32 v40, 0, v40
	v_add_f32_e32 v37, 1.0, v41
	v_mul_f32_e32 v41, 0x3e000000, v49
	v_fmac_f32_e32 v40, 0x3f317218, v44
	v_mul_f32_e64 v44, |v41|, s38
	v_exp_f32_e32 v44, v44
	v_max_f32_e32 v187, 0, v41
	v_mul_f32_e32 v41, 0x3e000000, v50
	v_sub_f32_e32 v170, 0, v40
; DI float fexp2(float x) { return __builtin_amdgcn_exp2f(x); }
; DI float flog2(float x) { return __builtin_amdgcn_logf(x); }
;     ...
;         if (MODE == 0) {
;           float Gs[8]; float lk[2][16];
; #pragma unroll
;           for (int j = 0; j < 2; ++j)
; #pragma unroll
;             for (int g = 0; g < 4; ++g) {
;               float gsum = 0.f;
; #pragma unroll
;               for (int e = 0; e < 4; ++e) {
;                 const int i = 4 * g + e;
;                 const float z = s[j][i] * 0.125f;
;                 const float sp = fmaxf(z, 0.f) + 0.69314718f * flog2(1.f + fexp2(-fabsf(z) * LOG2E));
;                 const bool valid = (kbase + j * 32 + 8 * g + e) < posq;
;                 const float l = valid ? -sp : 0.f;
;                 lk[j][i] = l; gsum += l;
;                 s[j][i] = z - sp;
;               }
;               Gs[j * 4 + g] = gsum;
;             }
;           float inc[9]; float run = 0.f; inc[8] = 0.f;
; #pragma unroll
;           for (int q = 7; q >= 0; --q) { run += Gs[q]; inc[q] = run; }
;           float recv[8];
; #pragma unroll
;           for (int q = 0; q < 8; ++q) recv[q] = __shfl_xor(inc[q + 1] + (hh ? Gs[q] : 0.f), 32);
;           const float ptot = __shfl_xor(run, 32);
	v_fma_f32 v171, v48, s3, -v40
	v_add_f32_e32 v40, 1.0, v44
	v_mul_f32_e64 v44, |v41|, s38
	v_log_f32_e32 v40, v40
	v_exp_f32_e32 v44, v44
	v_fma_f32 v166, v45, s3, -v165
	v_fma_f32 v168, v46, s3, -v167
	v_fmac_f32_e32 v187, 0x3f317218, v40
	v_max_f32_e32 v40, 0, v41
	v_add_f32_e32 v41, 1.0, v44
	v_log_f32_e32 v44, v41
	v_mul_f32_e32 v41, 0x3e000000, v51
	v_mul_f32_e64 v45, |v41|, s38
	v_exp_f32_e32 v45, v45
	v_mul_f32_e32 v46, 0x3e000000, v52
	v_mul_f32_e64 v48, |v46|, s38
	v_exp_f32_e32 v48, v48
	v_add_f32_e32 v45, 1.0, v45
	v_log_f32_e32 v45, v45
	v_max_f32_e32 v189, 0, v41
	v_add_f32_e32 v41, 1.0, v48
	v_log_f32_e32 v41, v41
	v_fmac_f32_e32 v189, 0x3f317218, v45
	v_max_f32_e32 v45, 0, v46
	v_mul_f32_e32 v46, 0x3e000000, v54
	v_mul_f32_e64 v48, |v46|, s38
	v_exp_f32_e32 v48, v48
	v_fmac_f32_e32 v45, 0x3f317218, v41
	v_mul_f32_e32 v41, 0x3e000000, v53
	v_max_f32_e32 v194, 0, v46
	v_mul_f32_e32 v46, 0x3e000000, v56
	v_fma_f32 v190, v51, s3, -v189
	v_sub_f32_e32 v51, 0, v45
	v_fma_f32 v191, v52, s3, -v45
	v_mul_f32_e64 v45, |v41|, s38
	v_max_f32_e32 v192, 0, v41
	v_add_f32_e32 v41, 1.0, v48
	v_mul_f32_e64 v48, |v46|, s38
	v_exp_f32_e32 v45, v45
	v_exp_f32_e32 v48, v48
	v_fma_f32 v188, v49, s3, -v187
	v_mul_f32_e32 v49, 0x3e000000, v57
	v_add_f32_e32 v45, 1.0, v45
	v_add_f32_e32 v48, 1.0, v48
	v_mul_f32_e64 v52, |v49|, s38
	v_log_f32_e32 v45, v45
	v_log_f32_e32 v48, v48
	v_exp_f32_e32 v52, v52
	v_max_f32_e32 v46, 0, v46
	v_fmac_f32_e32 v192, 0x3f317218, v45
	v_fmac_f32_e32 v46, 0x3f317218, v48
	v_add_f32_e32 v48, 1.0, v52
	v_mul_f32_e32 v52, 0x3e000000, v58
	v_fma_f32 v193, v53, s3, -v192
	v_log_f32_e32 v48, v48
	v_mul_f32_e64 v53, |v52|, s38
	v_exp_f32_e32 v53, v53
	v_max_f32_e32 v198, 0, v49
	v_fmac_f32_e32 v198, 0x3f317218, v48
	v_mul_f32_e32 v48, 0x3e000000, v59
	v_sub_f32_e32 v196, 0, v46
	v_fma_f32 v197, v56, s3, -v46
	v_add_f32_e32 v46, 1.0, v53
	v_mul_f32_e64 v49, |v48|, s38
	v_log_f32_e32 v46, v46
	v_exp_f32_e32 v49, v49
	v_max_f32_e32 v200, 0, v52
	v_max_f32_e32 v202, 0, v48
	v_fmac_f32_e32 v200, 0x3f317218, v46
	v_add_f32_e32 v46, 1.0, v49
	v_mul_f32_e32 v49, 0x3e000000, v60
	v_mul_f32_e64 v52, |v49|, s38
	v_log_f32_e32 v46, v46
	v_exp_f32_e32 v52, v52
	v_mul_f32_e32 v48, 0x3e000000, v61
	v_max_f32_e32 v49, 0, v49
	v_fmac_f32_e32 v202, 0x3f317218, v46
	v_add_f32_e32 v46, 1.0, v52
	v_mul_f32_e64 v52, |v48|, s38
	v_log_f32_e32 v46, v46
	v_exp_f32_e32 v52, v52
	v_max_f32_e32 v206, 0, v48
	v_max_f32_e32 v130, 0, v132
	v_fmac_f32_e32 v49, 0x3f317218, v46
	v_add_f32_e32 v46, 1.0, v52
	v_log_f32_e32 v46, v46
	v_sub_f32_e32 v204, 0, v49
	v_fma_f32 v205, v60, s3, -v49
	v_mul_f32_e32 v49, 0x3e000000, v63
	v_fmac_f32_e32 v206, 0x3f317218, v46
	v_mul_f32_e32 v46, 0x3e000000, v62
	v_mul_f32_e64 v48, |v46|, s38
	v_exp_f32_e32 v48, v48
	v_mul_f32_e64 v52, |v49|, s38
	v_mul_f32_e64 v132, |v132|, s38
	v_exp_f32_e32 v52, v52
	v_exp_f32_e32 v132, v132
	v_add_f32_e32 v48, 1.0, v48
	v_log_f32_e32 v48, v48
	v_max_f32_e32 v208, 0, v46
	v_add_f32_e32 v46, 1.0, v52
	v_add_f32_e32 v132, 1.0, v132
	v_log_f32_e32 v46, v46
	v_log_f32_e32 v132, v132
	v_fmac_f32_e32 v208, 0x3f317218, v48
	v_fma_f32 v209, v62, s3, -v208
	v_max_f32_e32 v62, 0, v49
	v_fmac_f32_e32 v62, 0x3f317218, v46
	v_or_b32_e32 v46, 1, v211
	v_cmp_lt_i32_e64 s[84:85], v46, v122
	v_pk_fma_f32 v[52:53], v[132:133], s[28:29], v[130:131] op_sel_hi:[1,0,1]
	v_log_f32_e32 v41, v41
	v_cndmask_b32_e64 v48, 0, -v157, s[84:85]
	v_fma_f32 v157, v34, s3, -v52
	v_or_b32_e32 v34, 3, v211
	v_cmp_lt_i32_e64 s[4:5], v34, v122
	v_or_b32_e32 v34, 8, v211
	v_cmp_lt_i32_e64 s[78:79], v34, v122
	v_fmac_f32_e32 v194, 0x3f317218, v41
	v_fma_f32 v199, v57, s3, -v198
	v_cndmask_b32_e64 v34, 0, v35, s[78:79]
	v_or_b32_e32 v35, 9, v211
	v_cmp_lt_i32_e64 s[80:81], v35, v122
	v_cndmask_b32_e64 v56, 0, v169, s[94:95]
	v_fma_f32 v195, v54, s3, -v194
	v_cndmask_b32_e64 v212, 0, -v159, s[80:81]
	v_add_f32_e32 v49, v212, v34
	v_or_b32_e32 v34, 10, v211
	v_cmp_lt_i32_e64 s[90:91], v34, v113
	v_or_b32_e32 v54, 2, v211
	v_cmp_lt_i32_e64 s[8:9], v54, v122
	v_cndmask_b32_e64 v57, 0, -v160, s[90:91]
	v_pk_add_f32 v[34:35], v[56:57], v[48:49]
	v_or_b32_e32 v49, 11, v211
	v_cmp_lt_i32_e64 s[40:41], v49, v113
	v_mul_f32_e32 v41, 0x3e000000, v55
	v_fma_f32 v201, v58, s3, -v200
	v_fma_f32 v203, v59, s3, -v202
	v_cndmask_b32_e64 v59, 0, -v53, s[40:41]
	v_cndmask_b32_e64 v58, 0, -v52, s[8:9]
	v_mul_f32_e64 v45, |v41|, s38
	v_fma_f32 v207, v61, s3, -v206
	v_pk_add_f32 v[60:61], v[58:59], v[34:35]
	v_or_b32_e32 v34, 17, v211
	v_or_b32_e32 v35, 25, v211
	v_exp_f32_e32 v45, v45
	v_fma_f32 v49, v39, s3, -v53
	v_cmp_lt_i32_e64 s[82:83], v34, v122
	v_or_b32_e32 v34, 19, v211
	v_cmp_lt_i32_e64 s[74:75], v35, v122
	v_or_b32_e32 v35, 40, v211
	v_or_b32_e32 v39, 41, v211
	v_cmp_lt_i32_e64 s[92:93], v34, v122
	v_or_b32_e32 v34, 24, v211
	v_cmp_lt_i32_e64 s[58:59], v35, v122
	v_cmp_lt_i32_e64 s[62:63], v39, v122
	v_cmp_lt_i32_e64 s[72:73], v34, v122
	v_cndmask_b32_e64 v56, 0, -v165, s[74:75]
	v_cndmask_b32_e64 v35, 0, v51, s[58:59]
	v_cndmask_b32_e64 v165, 0, -v192, s[62:63]
	v_cndmask_b32_e64 v34, 0, v163, s[72:73]
	v_add_f32_e32 v39, v165, v35
	v_or_b32_e32 v35, 48, v211
	v_or_b32_e32 v51, 49, v211
	v_add_f32_e32 v45, 1.0, v45
	v_add_f32_e32 v53, v56, v34
	v_or_b32_e32 v34, 33, v211
	v_cmp_lt_i32_e64 s[54:55], v35, v122
	v_cmp_lt_i32_e64 s[56:57], v51, v122
	v_or_b32_e32 v51, 50, v211
	v_log_f32_e32 v45, v45
	v_cmp_lt_i32_e64 s[70:71], v34, v122
	v_or_b32_e32 v34, 35, v211
	v_cndmask_b32_e64 v35, 0, v196, s[54:55]
	v_cndmask_b32_e64 v169, 0, -v198, s[56:57]
	v_cmp_lt_i32_e64 s[66:67], v51, v122
	v_or_b32_e32 v51, 51, v211
	v_cndmask_b32_e64 v52, 0, -v38, s[82:83]
; DI float fexp2(float x) { return __builtin_amdgcn_exp2f(x); }
;     ...
;           float inc[9]; float run = 0.f; inc[8] = 0.f;
; #pragma unroll
;           for (int q = 7; q >= 0; --q) { run += Gs[q]; inc[q] = run; }
;           float recv[8];
; #pragma unroll
;           for (int q = 0; q < 8; ++q) recv[q] = __shfl_xor(inc[q + 1] + (hh ? Gs[q] : 0.f), 32);
;           const float ptot = __shfl_xor(run, 32);
; #pragma unroll
;           for (int j = 0; j < 2; ++j)
; #pragma unroll
;             for (int g = 0; g < 4; ++g) {
;               const int q = j * 4 + g;
;               float later = Rrun + inc[q + 1] + recv[q];
; #pragma unroll
;               for (int e = 3; e >= 0; --e) {
;                 const int i = 4 * g + e;
;                 const bool valid = (kbase + j * 32 + 8 * g + e) < posq;
;                 const float a = valid ? fexp2((s[j][i] + later) * LOG2E) : 0.f;
;                 later += lk[j][i];
;                 s[j][i] = a;
;               }
;             }
	v_cndmask_b32_e64 v38, 0, -v187, s[70:71]
	v_cmp_lt_i32_e64 s[76:77], v34, v122
	v_add_f32_e32 v35, v169, v35
	v_cndmask_b32_e64 v187, 0, -v200, s[66:67]
	v_cmp_lt_i32_e64 s[68:69], v51, v122
	v_cndmask_b32_e64 v34, 0, -v189, s[76:77]
	v_add_f32_e32 v35, v187, v35
	v_cndmask_b32_e64 v189, 0, -v202, s[68:69]
	v_max_f32_e32 v41, 0, v41
	v_add_f32_e32 v192, v189, v35
	v_or_b32_e32 v35, 56, v211
	v_cmp_lt_i32_e32 vcc, v35, v122
	v_pk_fma_f32 v[40:41], v[44:45], s[28:29], v[40:41] op_sel_hi:[1,0,1]
	v_log_f32_e32 v37, v37
	v_cndmask_b32_e32 v35, 0, v204, vcc
	v_or_b32_e32 v51, 57, v211
	v_fma_f32 v204, v50, s3, -v40
	v_or_b32_e32 v44, 42, v211
	v_or_b32_e32 v50, 32, v211
	v_cmp_lt_i32_e64 s[52:53], v51, v122
	v_or_b32_e32 v51, 58, v211
	v_cmp_lt_i32_e64 s[86:87], v44, v113
	v_cmp_lt_i32_e64 s[88:89], v50, v122
	v_cmp_lt_i32_e64 s[60:61], v51, v122
	v_or_b32_e32 v51, 59, v211
	v_cndmask_b32_e64 v45, 0, -v194, s[86:87]
	v_cndmask_b32_e64 v44, 0, v170, s[88:89]
	v_max_f32_e32 v33, 0, v33
	v_cndmask_b32_e64 v196, 0, -v206, s[52:53]
	v_cmp_lt_i32_e64 s[64:65], v51, v122
	v_pk_add_f32 v[50:51], v[44:45], v[38:39]
	v_or_b32_e32 v44, 34, v211
	v_add_f32_e32 v35, v196, v35
	v_cndmask_b32_e64 v198, 0, -v208, s[60:61]
	v_or_b32_e32 v39, 43, v211
	v_cmp_lt_i32_e64 s[6:7], v44, v122
	v_pk_fma_f32 v[32:33], v[36:37], s[28:29], v[32:33] op_sel_hi:[1,0,1]
	v_or_b32_e32 v36, 26, v211
	v_or_b32_e32 v44, 16, v211
	v_add_f32_e32 v35, v198, v35
	v_cndmask_b32_e64 v200, 0, -v62, s[64:65]
	v_cmp_lt_i32_e64 s[96:97], v39, v113
	v_cmp_lt_i32_e64 s[10:11], v36, v113
	v_cmp_lt_i32_e64 s[12:13], v44, v122
	v_add_f32_e32 v202, v200, v35
	v_fma_f32 v206, v55, s3, -v41
	v_cndmask_b32_e64 v41, 0, -v41, s[96:97]
	v_cndmask_b32_e64 v40, 0, -v40, s[6:7]
	v_cndmask_b32_e64 v37, 0, -v167, s[10:11]
	v_cndmask_b32_e64 v36, 0, v161, s[12:13]
	v_add_f32_e32 v35, v202, v192
	v_pk_add_f32 v[50:51], v[40:41], v[50:51]
	v_pk_add_f32 v[132:133], v[36:37], v[52:53]
	v_or_b32_e32 v36, 27, v211
	v_or_b32_e32 v44, 18, v211
	v_fma_f32 v210, v63, s3, -v62
	v_pk_add_f32 v[62:63], v[34:35], v[50:51]
	v_cmp_lt_i32_e64 s[14:15], v36, v113
	v_cmp_lt_i32_e64 s[16:17], v44, v122
	v_pk_add_f32 v[130:131], v[62:63], v[62:63] op_sel:[0,1] op_sel_hi:[1,0]
	v_fma_f32 v39, v42, s3, -v32
	v_fma_f32 v42, v47, s3, -v33
	v_cndmask_b32_e64 v33, 0, -v33, s[14:15]
	v_cndmask_b32_e64 v32, 0, -v32, s[16:17]
	v_cndmask_b32_e64 v54, 0, -v162, s[92:93]
	v_pk_add_f32 v[132:133], v[32:33], v[132:133]
	v_mov_b32_e32 v55, v130
	v_cndmask_b32_e64 v46, 0, -v158, s[4:5]
	v_pk_add_f32 v[158:159], v[54:55], v[132:133]
	v_and_b32_e32 v44, 64, v182
	v_pk_add_f32 v[160:161], v[158:159], v[158:159] op_sel:[0,1] op_sel_hi:[1,0]
	v_xor_b32_e32 v36, 32, v182
	v_mov_b32_e32 v47, v160
	v_add_u32_e32 v44, 64, v44
	v_pk_add_f32 v[162:163], v[46:47], v[60:61]
	v_cmp_lt_i32_e64 s[20:21], v36, v44
	v_cndmask_b32_e64 v44, v162, 0, s[46:47]
	v_add_f32_e32 v44, v44, v163
	v_cndmask_b32_e64 v36, v182, v36, s[20:21]
	v_lshlrev_b32_e32 v36, 2, v36
	ds_bpermute_b32 v44, v36, v44
	v_add_f32_e32 v131, v141, v163
	v_cndmask_b32_e64 v47, v61, 0, s[46:47]
	v_cndmask_b32_e64 v53, v158, 0, s[46:47]
	v_cndmask_b32_e64 v55, v133, 0, s[46:47]
	s_waitcnt lgkmcnt(0)
	v_add_f32_e32 v44, v131, v44
	v_cndmask_b32_e64 v60, v62, 0, s[46:47]
	v_cndmask_b32_e64 v51, v51, 0, s[46:47]
	v_cndmask_b32_e64 v61, v192, 0, s[46:47]
	v_add_f32_e32 v131, v155, v44
	v_add_f32_e32 v44, v46, v44
	v_add_f32_e32 v50, v162, v163
	v_add_f32_e32 v47, v47, v160
	v_add_f32_e32 v53, v53, v159
	v_add_f32_e32 v55, v55, v130
	v_add_f32_e32 v60, v60, v63
	v_add_f32_e32 v51, v35, v51
	v_add_f32_e32 v61, v202, v61
	v_cndmask_b32_e64 v62, v202, 0, s[46:47]
	v_add_f32_e32 v46, v157, v44
	ds_bpermute_b32 v47, v36, v47
	ds_bpermute_b32 v53, v36, v53
	ds_bpermute_b32 v55, v36, v55
	ds_bpermute_b32 v60, v36, v60
	ds_bpermute_b32 v51, v36, v51
	ds_bpermute_b32 v61, v36, v61
	v_mul_f32_e32 v46, 0x3fb8aa3b, v46
	ds_bpermute_b32 v62, v36, v62
	ds_bpermute_b32 v132, v36, v50
	v_add_f32_e32 v36, v58, v44
	v_exp_f32_e32 v46, v46
	v_add_f32_e32 v44, v152, v36
	v_add_f32_e32 v36, v48, v36
	v_add_f32_e32 v36, v143, v36
	v_mul_f32_e32 v36, 0x3fb8aa3b, v36
	v_mul_f32_e32 v44, 0x3fb8aa3b, v44
	v_exp_f32_e32 v36, v36
	v_cndmask_b32_e64 v133, 0, v46, s[8:9]
	v_exp_f32_e32 v44, v44
	v_add_f32_e32 v46, v141, v160
	s_waitcnt lgkmcnt(7)
	v_add_f32_e32 v46, v46, v47
	v_add_f32_e32 v47, v49, v46
	v_add_f32_e32 v46, v59, v46
	v_mul_f32_e32 v47, 0x3fb8aa3b, v47
	v_cndmask_b32_e64 v58, 0, v36, s[94:95]
	v_add_f32_e32 v36, v57, v46
	v_exp_f32_e32 v47, v47
	v_cndmask_b32_e64 v49, 0, v44, s[84:85]
	v_add_f32_e32 v44, v150, v36
	v_add_f32_e32 v36, v212, v36
	v_add_f32_e32 v36, v142, v36
	v_add_f32_e32 v48, v154, v46
	v_mul_f32_e32 v36, 0x3fb8aa3b, v36
	v_add_f32_e32 v46, v141, v159
	v_exp_f32_e32 v36, v36
	s_waitcnt lgkmcnt(6)
	v_add_f32_e32 v46, v46, v53
	v_cndmask_b32_e64 v59, 0, v47, s[40:41]
	v_add_f32_e32 v47, v164, v46
	v_add_f32_e32 v46, v54, v46
	v_add_f32_e32 v39, v39, v46
	v_mul_f32_e32 v39, 0x3fb8aa3b, v39
	v_add_f32_e32 v32, v32, v46
	v_exp_f32_e32 v39, v39
	v_cndmask_b32_e64 v54, 0, v36, s[78:79]
	v_add_f32_e32 v36, v156, v32
	v_add_f32_e32 v32, v52, v32
	v_add_f32_e32 v32, v153, v32
	v_mul_f32_e32 v32, 0x3fb8aa3b, v32
	v_exp_f32_e32 v32, v32
	v_cndmask_b32_e64 v142, 0, v39, s[16:17]
	v_add_f32_e32 v39, v141, v130
	s_waitcnt lgkmcnt(5)
	v_add_f32_e32 v39, v39, v55
	v_add_f32_e32 v33, v33, v39
	v_mul_f32_e32 v36, 0x3fb8aa3b, v36
	v_cndmask_b32_e64 v55, 0, v32, s[12:13]
	v_add_f32_e32 v32, v37, v33
	v_exp_f32_e32 v36, v36
	v_add_f32_e32 v42, v42, v39
	v_add_f32_e32 v39, v168, v33
	v_add_f32_e32 v33, v166, v32
	v_add_f32_e32 v32, v56, v32
	v_add_f32_e32 v32, v43, v32
	v_mul_f32_e32 v32, 0x3fb8aa3b, v32
	v_mul_f32_e32 v33, 0x3fb8aa3b, v33
	v_exp_f32_e32 v32, v32
	v_cndmask_b32_e64 v52, 0, v36, s[82:83]
	v_exp_f32_e32 v33, v33
	v_add_f32_e32 v36, v141, v63
	s_waitcnt lgkmcnt(4)
; #define MFMA32(a, b, c) __builtin_amdgcn_mfma_f32_32x32x16_bf16((a), (b), (c), 0, 0, 0)
; DI float fexp2(float x) { return __builtin_amdgcn_exp2f(x); }
;     ...
;         auto ldv = [&](int j) {
; #pragma unroll
;           for (int st = 0; st < 2; ++st)
; #pragma unroll
;             for (int dt = 0; dt < 2; ++dt) {
;               const bf16_t* vp = Vb + (dt * 32 + r) * VST + j * 32 + 16 * st + 4 * hh;
;               const u32x2 lo = *(const u32x2*)vp, hi = *(const u32x2*)(vp + 8);
;               vfr[st][dt][0] = lo[0]; vfr[st][dt][1] = lo[1]; vfr[st][dt][2] = hi[0]; vfr[st][dt][3] = hi[1];
;             }
;           __builtin_amdgcn_sched_barrier(0);
;         };
;         auto pvm = [&](int j) {
; #pragma unroll
;           for (int st = 0; st < 2; ++st) {
;             u32x4 pp;
; #pragma unroll
;             for (int q = 0; q < 4; ++q) pp[q] = pk_bf16(s[j][8 * st + 2 * q], s[j][8 * st + 2 * q + 1]);
;             const bf16x8 pb = __builtin_bit_cast(bf16x8, pp);
; #pragma unroll
;             for (int dt = 0; dt < 2; ++dt) oacc[dt] = MFMA32(__builtin_bit_cast(bf16x8, vfr[st][dt]), pb, oacc[dt]);
;           }
;         };
;         auto pv = [&](int j) { ldv(j); pvm(j); };
;     ...
;           for (int j = 0; j < 2; ++j)
; #pragma unroll
;             for (int g = 0; g < 4; ++g) {
;               const int q = j * 4 + g;
;               float later = Rrun + inc[q + 1] + recv[q];
; #pragma unroll
;               for (int e = 3; e >= 0; --e) {
;                 const int i = 4 * g + e;
;                 const bool valid = (kbase + j * 32 + 8 * g + e) < posq;
;                 const float a = valid ? fexp2((s[j][i] + later) * LOG2E) : 0.f;
;                 later += lk[j][i];
;                 s[j][i] = a;
;               }
;             }
;           Rrun += run + ptot;
	v_add_f32_e32 v36, v36, v60
	v_add_f32_e32 v34, v34, v36
	v_cndmask_b32_e64 v60, 0, v32, s[72:73]
	v_add_f32_e32 v32, v40, v34
	v_cndmask_b32_e64 v56, 0, v33, s[74:75]
	v_add_f32_e32 v33, v188, v32
	v_add_f32_e32 v32, v38, v32
	v_add_f32_e32 v32, v171, v32
	v_mul_f32_e32 v32, 0x3fb8aa3b, v32
	v_add_f32_e32 v37, v190, v36
	v_add_f32_e32 v36, v204, v34
	v_mul_f32_e32 v33, 0x3fb8aa3b, v33
	v_exp_f32_e32 v32, v32
	v_mul_f32_e32 v36, 0x3fb8aa3b, v36
	v_exp_f32_e32 v33, v33
	v_add_f32_e32 v34, v141, v35
	v_exp_f32_e32 v36, v36
	s_waitcnt lgkmcnt(3)
	v_add_f32_e32 v34, v34, v51
	v_add_f32_e32 v35, v206, v34
	v_add_f32_e32 v34, v41, v34
	v_cndmask_b32_e64 v154, 0, v32, s[88:89]
	v_add_f32_e32 v32, v45, v34
	v_cndmask_b32_e64 v153, 0, v33, s[70:71]
	v_add_f32_e32 v33, v193, v32
	v_add_f32_e32 v32, v165, v32
	v_cndmask_b32_e64 v152, 0, v36, s[6:7]
	v_mul_f32_e32 v35, 0x3fb8aa3b, v35
	v_add_f32_e32 v36, v195, v34
	v_add_f32_e32 v32, v191, v32
	v_exp_f32_e32 v35, v35
	v_mul_f32_e32 v36, 0x3fb8aa3b, v36
	v_mul_f32_e32 v32, 0x3fb8aa3b, v32
	v_exp_f32_e32 v36, v36
	v_mul_f32_e32 v33, 0x3fb8aa3b, v33
	v_exp_f32_e32 v32, v32
	v_exp_f32_e32 v33, v33
	v_add_f32_e32 v34, v141, v202
	s_waitcnt lgkmcnt(2)
	v_add_f32_e32 v34, v34, v61
	v_cndmask_b32_e64 v155, 0, v35, s[96:97]
	v_add_f32_e32 v35, v203, v34
	v_add_f32_e32 v34, v189, v34
	v_cndmask_b32_e64 v156, 0, v36, s[86:87]
	v_mul_f32_e32 v35, 0x3fb8aa3b, v35
	v_add_f32_e32 v36, v201, v34
	v_cndmask_b32_e64 v157, 0, v32, s[58:59]
	v_add_f32_e32 v32, v187, v34
	v_exp_f32_e32 v35, v35
	v_mul_f32_e32 v36, 0x3fb8aa3b, v36
	v_cndmask_b32_e64 v61, 0, v33, s[62:63]
	v_add_f32_e32 v33, v199, v32
	v_add_f32_e32 v32, v169, v32
	v_exp_f32_e32 v36, v36
	v_add_f32_e32 v32, v197, v32
	v_mul_f32_e32 v32, 0x3fb8aa3b, v32
	v_add_f32_e32 v34, 0, v141
	v_mul_f32_e32 v33, 0x3fb8aa3b, v33
	v_exp_f32_e32 v32, v32
	s_waitcnt lgkmcnt(1)
	v_add_f32_e32 v34, v34, v62
	v_cndmask_b32_e64 v158, 0, v35, s[68:69]
	v_exp_f32_e32 v33, v33
	v_add_f32_e32 v35, v210, v34
	v_add_f32_e32 v34, v200, v34
	v_mul_f32_e32 v48, 0x3fb8aa3b, v48
	v_cndmask_b32_e64 v159, 0, v36, s[66:67]
	v_add_f32_e32 v36, v209, v34
	v_exp_f32_e32 v48, v48
	v_mul_f32_e32 v44, 0x3fb8aa3b, v44
	v_mul_f32_e32 v47, 0x3fb8aa3b, v47
	v_mul_f32_e32 v42, 0x3fb8aa3b, v42
	v_mul_f32_e32 v39, 0x3fb8aa3b, v39
	v_mul_f32_e32 v37, 0x3fb8aa3b, v37
	v_mul_f32_e32 v35, 0x3fb8aa3b, v35
	v_mul_f32_e32 v36, 0x3fb8aa3b, v36
	v_exp_f32_e32 v44, v44
	v_exp_f32_e32 v47, v47
	v_exp_f32_e32 v42, v42
	v_exp_f32_e32 v39, v39
	v_exp_f32_e32 v37, v37
	v_exp_f32_e32 v35, v35
	v_exp_f32_e32 v36, v36
	v_cndmask_b32_e64 v160, 0, v32, s[54:55]
	v_add_f32_e32 v32, v198, v34
	v_cndmask_b32_e64 v62, 0, v33, s[56:57]
	v_add_f32_e32 v33, v207, v32
	v_add_f32_e32 v32, v196, v32
	v_mul_f32_e32 v33, 0x3fb8aa3b, v33
	v_add_f32_e32 v32, v205, v32
	v_cndmask_b32_e64 v143, 0, v48, s[90:91]
	v_exp_f32_e32 v48, v33
	v_mul_f32_e32 v32, 0x3fb8aa3b, v32
	v_add_u32_e32 v163, 0x6800, v138
	v_add_u32_e32 v164, 0x7800, v138
	v_mul_f32_e32 v131, 0x3fb8aa3b, v131
	v_cndmask_b32_e64 v53, 0, v44, s[80:81]
	v_cndmask_b32_e64 v57, 0, v47, s[92:93]
	v_cndmask_b32_e64 v130, 0, v42, s[14:15]
	v_cndmask_b32_e64 v150, 0, v39, s[10:11]
	v_cndmask_b32_e64 v63, 0, v37, s[76:77]
	v_cndmask_b32_e64 v161, 0, v35, s[64:65]
	v_cndmask_b32_e64 v162, 0, v36, s[60:61]
	v_exp_f32_e32 v51, v32
	ds_read_b128 v[32:35], v138 offset:36864
	ds_read_b128 v[36:39], v138 offset:36896
	ds_read_b128 v[40:43], v138 offset:41472
	ds_read_b128 v[44:47], v138 offset:41504
	v_exp_f32_e32 v131, v131
	v_readlane_b32 s56, v223, 13
	v_cndmask_b32_e64 v165, 0, v48, s[52:53]
	s_waitcnt lgkmcnt(4)
	v_add_f32_e32 v48, v50, v132
	s_movk_i32 s73, 0x600
	s_mov_b32 s72, 0xfffffc0
	v_readlane_b32 s57, v223, 14
	v_readlane_b32 s58, v223, 15
	v_readlane_b32 s59, v223, 16
	v_readlane_b32 s60, v223, 17
	v_readlane_b32 s61, v223, 18
	v_readlane_b32 s62, v223, 19
	v_readlane_b32 s63, v223, 20
	v_readlane_b32 s64, v223, 21
	v_readlane_b32 s65, v223, 22
	v_readlane_b32 s66, v223, 23
	v_readlane_b32 s67, v223, 24
	v_readlane_b32 s68, v223, 25
	v_readlane_b32 s69, v223, 26
	v_readlane_b32 s70, v223, 27
	v_readlane_b32 s71, v223, 28
	v_add_f32_e32 v141, v141, v48
	v_cndmask_b32_e64 v131, 0, v131, s[4:5]
	v_cndmask_b32_e32 v166, 0, v51, vcc
	v_cvt_pk_bf16_f32 v48, v58, v49
	v_cvt_pk_bf16_f32 v49, v133, v131
	v_cvt_pk_bf16_f32 v50, v54, v53
	v_cvt_pk_bf16_f32 v51, v143, v59
	s_waitcnt lgkmcnt(3)
	s_nop 0
	v_mfma_f32_32x32x16_bf16 v[16:31], v[32:35], v[48:51], v[16:31]
	v_cvt_pk_bf16_f32 v32, v55, v52
	v_cvt_pk_bf16_f32 v33, v142, v57
	v_cvt_pk_bf16_f32 v34, v60, v56
	v_cvt_pk_bf16_f32 v35, v150, v130
	s_waitcnt lgkmcnt(1)
	v_mfma_f32_32x32x16_bf16 v[0:15], v[40:43], v[48:51], v[0:15]
	v_mfma_f32_32x32x16_bf16 v[16:31], v[36:39], v[32:35], v[16:31]
	s_waitcnt lgkmcnt(0)
	v_mfma_f32_32x32x16_bf16 v[0:15], v[44:47], v[32:35], v[0:15]
	ds_read_b128 v[32:35], v138 offset:36928
	ds_read_b128 v[36:39], v138 offset:36960
	ds_read_b128 v[40:43], v138 offset:41536
	ds_read_b128 v[44:47], v138 offset:41568
	v_cvt_pk_bf16_f32 v48, v154, v153
	v_cvt_pk_bf16_f32 v49, v152, v63
	v_cvt_pk_bf16_f32 v50, v157, v61
	v_cvt_pk_bf16_f32 v51, v156, v155
	s_waitcnt lgkmcnt(3)
	s_nop 0
	v_mfma_f32_32x32x16_bf16 v[16:31], v[32:35], v[48:51], v[16:31]
	v_cvt_pk_bf16_f32 v32, v160, v62
	v_cvt_pk_bf16_f32 v33, v159, v158
	v_cvt_pk_bf16_f32 v34, v166, v165
	v_cvt_pk_bf16_f32 v35, v162, v161
	s_waitcnt lgkmcnt(1)
	v_mfma_f32_32x32x16_bf16 v[0:15], v[40:43], v[48:51], v[0:15]
	v_mfma_f32_32x32x16_bf16 v[16:31], v[36:39], v[32:35], v[16:31]
	s_waitcnt lgkmcnt(0)
	v_mfma_f32_32x32x16_bf16 v[0:15], v[44:47], v[32:35], v[0:15]
.LBB0_1137:
	s_or_b64 exec, exec, s[24:25]
	s_add_i32 s6, s1, -1
	s_cmp_lt_i32 s1, 1
	s_waitcnt vmcnt(7)
	ds_write_b128 v112, v[80:83]
	s_waitcnt vmcnt(6)
	ds_write_b128 v112, v[84:87] offset:64
	s_waitcnt vmcnt(5)
	ds_write2_b64 v121, v[88:89], v[90:91] offset1:2
	s_waitcnt vmcnt(4)
	ds_write2_b64 v139, v[92:93], v[94:95] offset1:2
	s_cselect_b64 s[4:5], -1, 0
	s_mov_b32 s1, s6
	s_branch .LBB0_1123
